# hand-written pipelined final rmsnorm phase + S5 input prefetch + first 2 MFMAs of each block hoisted above barrier
# baseline (speedup 1.0000x reference)
.LBB0_115:
	ds_read_b128 v[144:147], v151
	ds_read_b128 v[154:157], v151 offset:1024
	ds_read_b128 v[158:161], v151 offset:2048
	ds_read_b128 v[162:165], v151 offset:3072
	ds_read_b128 v[166:169], v152
	ds_read_b128 v[170:173], v152 offset:1024
	ds_read_b128 v[174:177], v152 offset:2048
	ds_read_b128 v[178:181], v152 offset:3072
	s_add_u32 s66, s64, 0xfff80080
	s_addc_u32 s67, s65, -1
	s_cmp_eq_u32 s86, 28
	s_cselect_b32 s69, s27, s67
	s_cselect_b32 s68, s82, s66
	s_cselect_b32 s67, s25, s85
	s_cselect_b32 s66, s83, s84
	v_lshl_add_u64 v[210:211], s[64:65], 0, v[136:137]
	s_add_i32 m0, s41, 0xc000
	ds_read_b128 v[182:185], v153
	ds_read_b128 v[186:189], v153 offset:1024
	ds_read_b128 v[190:193], v153 offset:2048
	ds_read_b128 v[194:197], v153 offset:3072
	ds_read_b128 v[198:201], v153 offset:4096
	ds_read_b128 v[202:205], v153 offset:5120
	ds_read_b128 v[206:209], v153 offset:6144
	ds_read_b128 v[214:217], v153 offset:7168
	global_load_lds_dwordx4 v[210:211], off
	v_lshl_add_u64 v[210:211], s[64:65], 0, v[138:139]
	s_add_i32 m0, s41, 0xe000
	s_nop 0
	global_load_lds_dwordx4 v[210:211], off
	s_waitcnt vmcnt(8)
	s_waitcnt lgkmcnt(0)
	v_mfma_f32_16x16x32_bf16 v[124:127], v[144:147], v[182:185], v[124:127]
	v_mfma_f32_16x16x32_bf16 v[120:123], v[158:161], v[182:185], v[120:123]
	s_barrier
	s_setprio 1
	s_waitcnt lgkmcnt(0)
	v_mfma_f32_16x16x32_bf16 v[116:119], v[144:147], v[190:193], v[116:119]
	v_mfma_f32_16x16x32_bf16 v[112:115], v[158:161], v[190:193], v[112:115]
	v_mfma_f32_16x16x32_bf16 v[100:103], v[144:147], v[198:201], v[100:103]
	v_mfma_f32_16x16x32_bf16 v[96:99], v[158:161], v[198:201], v[96:99]
	v_mfma_f32_16x16x32_bf16 v[76:79], v[144:147], v[206:209], v[76:79]
	v_mfma_f32_16x16x32_bf16 v[72:75], v[158:161], v[206:209], v[72:75]
	v_mfma_f32_16x16x32_bf16 v[124:127], v[154:157], v[186:189], v[124:127]
	v_mfma_f32_16x16x32_bf16 v[120:123], v[162:165], v[186:189], v[120:123]
	v_mfma_f32_16x16x32_bf16 v[116:119], v[154:157], v[194:197], v[116:119]
	v_mfma_f32_16x16x32_bf16 v[112:115], v[162:165], v[194:197], v[112:115]
	v_mfma_f32_16x16x32_bf16 v[100:103], v[154:157], v[202:205], v[100:103]
	v_mfma_f32_16x16x32_bf16 v[96:99], v[162:165], v[202:205], v[96:99]
	v_mfma_f32_16x16x32_bf16 v[76:79], v[154:157], v[214:217], v[76:79]
	v_mfma_f32_16x16x32_bf16 v[72:75], v[162:165], v[214:217], v[72:75]
	s_setprio 0
	s_setprio 1
	v_mfma_f32_16x16x32_bf16 v[108:111], v[166:169], v[182:185], v[108:111]
	v_mfma_f32_16x16x32_bf16 v[104:107], v[174:177], v[182:185], v[104:107]
	v_mfma_f32_16x16x32_bf16 v[92:95], v[166:169], v[190:193], v[92:95]
	v_mfma_f32_16x16x32_bf16 v[88:91], v[174:177], v[190:193], v[88:91]
	v_mfma_f32_16x16x32_bf16 v[84:87], v[166:169], v[198:201], v[84:87]
	v_mfma_f32_16x16x32_bf16 v[80:83], v[174:177], v[198:201], v[80:83]
	v_mfma_f32_16x16x32_bf16 v[68:71], v[166:169], v[206:209], v[68:71]
	v_mfma_f32_16x16x32_bf16 v[64:67], v[174:177], v[206:209], v[64:67]
	v_mfma_f32_16x16x32_bf16 v[108:111], v[170:173], v[186:189], v[108:111]
	v_mfma_f32_16x16x32_bf16 v[104:107], v[178:181], v[186:189], v[104:107]
	v_mfma_f32_16x16x32_bf16 v[92:95], v[170:173], v[194:197], v[92:95]
	v_mfma_f32_16x16x32_bf16 v[88:91], v[178:181], v[194:197], v[88:91]
	v_mfma_f32_16x16x32_bf16 v[84:87], v[170:173], v[202:205], v[84:87]
	v_mfma_f32_16x16x32_bf16 v[80:83], v[178:181], v[202:205], v[80:83]
	v_mfma_f32_16x16x32_bf16 v[68:71], v[170:173], v[214:217], v[68:71]
	v_mfma_f32_16x16x32_bf16 v[64:67], v[178:181], v[214:217], v[64:67]
	s_setprio 0
	s_barrier
	s_add_i32 s87, s78, s3
	v_lshl_add_u64 v[210:211], s[66:67], 0, v[132:133]
	s_mov_b32 m0, s87
	ds_read_b128 v[182:185], v153 offset:16384
	ds_read_b128 v[186:189], v153 offset:17408
	ds_read_b128 v[190:193], v153 offset:18432
	ds_read_b128 v[194:197], v153 offset:19456
	ds_read_b128 v[198:201], v153 offset:20480
	ds_read_b128 v[202:205], v153 offset:21504
	ds_read_b128 v[206:209], v153 offset:22528
	ds_read_b128 v[214:217], v153 offset:23552
	global_load_lds_dwordx4 v[210:211], off
	s_add_i32 m0, s87, 0x2000
	s_add_u32 s88, s66, 0x80000
	v_lshl_add_u64 v[218:219], s[66:67], 0, v[128:129]
	s_addc_u32 s89, s67, 0
	s_add_i32 s87, s79, s3
	global_load_lds_dwordx4 v[218:219], off
	v_lshl_add_u64 v[220:221], s[88:89], 0, v[132:133]
	s_mov_b32 m0, s87
	v_lshl_add_u64 v[222:223], s[68:69], 0, v[130:131]
	global_load_lds_dwordx4 v[220:221], off
	v_lshl_add_u64 v[220:221], s[88:89], 0, v[128:129]
	s_add_i32 m0, s87, 0x2000
	s_nop 0
	global_load_lds_dwordx4 v[220:221], off
	v_lshl_add_u64 v[220:221], s[68:69], 0, v[134:135]
	s_mov_b32 m0, s41
	s_nop 0
	global_load_lds_dwordx4 v[220:221], off
	s_mov_b32 m0, s70
	s_nop 0
	global_load_lds_dwordx4 v[222:223], off
	s_waitcnt vmcnt(8)
	s_waitcnt lgkmcnt(0)
	v_mfma_f32_16x16x32_bf16 v[60:63], v[144:147], v[182:185], v[60:63]
	v_mfma_f32_16x16x32_bf16 v[56:59], v[158:161], v[182:185], v[56:59]
	s_barrier
	s_setprio 1
	s_waitcnt lgkmcnt(0)
	v_mfma_f32_16x16x32_bf16 v[52:55], v[144:147], v[190:193], v[52:55]
	v_mfma_f32_16x16x32_bf16 v[44:47], v[158:161], v[190:193], v[44:47]
	v_mfma_f32_16x16x32_bf16 v[36:39], v[144:147], v[198:201], v[36:39]
	v_mfma_f32_16x16x32_bf16 v[28:31], v[158:161], v[198:201], v[28:31]
	v_mfma_f32_16x16x32_bf16 v[20:23], v[144:147], v[206:209], v[20:23]
	v_mfma_f32_16x16x32_bf16 v[12:15], v[158:161], v[206:209], v[12:15]
	v_mfma_f32_16x16x32_bf16 v[60:63], v[154:157], v[186:189], v[60:63]
	v_mfma_f32_16x16x32_bf16 v[56:59], v[162:165], v[186:189], v[56:59]
	v_mfma_f32_16x16x32_bf16 v[52:55], v[154:157], v[194:197], v[52:55]
	v_mfma_f32_16x16x32_bf16 v[44:47], v[162:165], v[194:197], v[44:47]
	v_mfma_f32_16x16x32_bf16 v[36:39], v[154:157], v[202:205], v[36:39]
	v_mfma_f32_16x16x32_bf16 v[28:31], v[162:165], v[202:205], v[28:31]
	v_mfma_f32_16x16x32_bf16 v[20:23], v[154:157], v[214:217], v[20:23]
	v_mfma_f32_16x16x32_bf16 v[12:15], v[162:165], v[214:217], v[12:15]
	s_setprio 0
	s_setprio 1
	v_mfma_f32_16x16x32_bf16 v[48:51], v[166:169], v[182:185], v[48:51]
	v_mfma_f32_16x16x32_bf16 v[40:43], v[174:177], v[182:185], v[40:43]
	v_mfma_f32_16x16x32_bf16 v[32:35], v[166:169], v[190:193], v[32:35]
	v_mfma_f32_16x16x32_bf16 v[24:27], v[174:177], v[190:193], v[24:27]
	v_mfma_f32_16x16x32_bf16 v[16:19], v[166:169], v[198:201], v[16:19]
	v_mfma_f32_16x16x32_bf16 v[8:11], v[174:177], v[198:201], v[8:11]
	v_mfma_f32_16x16x32_bf16 v[4:7], v[166:169], v[206:209], v[4:7]
	v_mfma_f32_16x16x32_bf16 v[0:3], v[174:177], v[206:209], v[0:3]
	v_mfma_f32_16x16x32_bf16 v[48:51], v[170:173], v[186:189], v[48:51]
	v_mfma_f32_16x16x32_bf16 v[40:43], v[178:181], v[186:189], v[40:43]
	v_mfma_f32_16x16x32_bf16 v[32:35], v[170:173], v[194:197], v[32:35]
	v_mfma_f32_16x16x32_bf16 v[24:27], v[178:181], v[194:197], v[24:27]
	v_mfma_f32_16x16x32_bf16 v[16:19], v[170:173], v[202:205], v[16:19]
	v_mfma_f32_16x16x32_bf16 v[8:11], v[178:181], v[202:205], v[8:11]
	v_mfma_f32_16x16x32_bf16 v[4:7], v[170:173], v[214:217], v[4:7]
	v_mfma_f32_16x16x32_bf16 v[0:3], v[178:181], v[214:217], v[0:3]
	s_setprio 0
	s_barrier
	s_add_i32 s87, 0, 0x18000
	s_add_i32 s88, 0, 0x1c000
	v_add_u32_e32 v162, s87, v149
	v_add_u32_e32 v178, s88, v149
	ds_read_b128 v[144:147], v162
	ds_read_b128 v[154:157], v162 offset:1024
	ds_read_b128 v[158:161], v162 offset:2048
	ds_read_b128 v[162:165], v162 offset:3072
	ds_read_b128 v[166:169], v178
	ds_read_b128 v[170:173], v178 offset:1024
	ds_read_b128 v[174:177], v178 offset:2048
	ds_read_b128 v[178:181], v178 offset:3072
	s_add_u32 s68, s68, 0x80000
	s_addc_u32 s69, s69, 0
	s_mov_b32 m0, s71
	v_lshl_add_u64 v[224:225], s[68:69], 0, v[134:135]
	ds_read_b128 v[182:185], v153 offset:32768
	ds_read_b128 v[186:189], v153 offset:33792
	ds_read_b128 v[190:193], v153 offset:34816
	ds_read_b128 v[194:197], v153 offset:35840
	ds_read_b128 v[198:201], v153 offset:36864
	ds_read_b128 v[202:205], v153 offset:37888
	ds_read_b128 v[206:209], v153 offset:38912
	ds_read_b128 v[214:217], v153 offset:39936
	global_load_lds_dwordx4 v[224:225], off
	v_lshl_add_u64 v[224:225], s[68:69], 0, v[130:131]
	s_mov_b32 m0, s72
	s_nop 0
	global_load_lds_dwordx4 v[224:225], off
	s_waitcnt vmcnt(8)
	s_waitcnt lgkmcnt(0)
	v_mfma_f32_16x16x32_bf16 v[124:127], v[144:147], v[182:185], v[124:127]
	v_mfma_f32_16x16x32_bf16 v[120:123], v[158:161], v[182:185], v[120:123]
	s_barrier
	s_setprio 1
	s_waitcnt lgkmcnt(0)
	v_mfma_f32_16x16x32_bf16 v[116:119], v[144:147], v[190:193], v[116:119]
	v_mfma_f32_16x16x32_bf16 v[112:115], v[158:161], v[190:193], v[112:115]
	v_mfma_f32_16x16x32_bf16 v[100:103], v[144:147], v[198:201], v[100:103]
	v_mfma_f32_16x16x32_bf16 v[96:99], v[158:161], v[198:201], v[96:99]
	v_mfma_f32_16x16x32_bf16 v[76:79], v[144:147], v[206:209], v[76:79]
	v_mfma_f32_16x16x32_bf16 v[72:75], v[158:161], v[206:209], v[72:75]
	v_mfma_f32_16x16x32_bf16 v[124:127], v[154:157], v[186:189], v[124:127]
	v_mfma_f32_16x16x32_bf16 v[120:123], v[162:165], v[186:189], v[120:123]
	v_mfma_f32_16x16x32_bf16 v[116:119], v[154:157], v[194:197], v[116:119]
	v_mfma_f32_16x16x32_bf16 v[112:115], v[162:165], v[194:197], v[112:115]
	v_mfma_f32_16x16x32_bf16 v[100:103], v[154:157], v[202:205], v[100:103]
	v_mfma_f32_16x16x32_bf16 v[96:99], v[162:165], v[202:205], v[96:99]
	v_mfma_f32_16x16x32_bf16 v[76:79], v[154:157], v[214:217], v[76:79]
	v_mfma_f32_16x16x32_bf16 v[72:75], v[162:165], v[214:217], v[72:75]
	s_setprio 0
	s_setprio 1
	v_mfma_f32_16x16x32_bf16 v[108:111], v[166:169], v[182:185], v[108:111]
	v_mfma_f32_16x16x32_bf16 v[104:107], v[174:177], v[182:185], v[104:107]
	v_mfma_f32_16x16x32_bf16 v[92:95], v[166:169], v[190:193], v[92:95]
	v_mfma_f32_16x16x32_bf16 v[88:91], v[174:177], v[190:193], v[88:91]
	v_mfma_f32_16x16x32_bf16 v[84:87], v[166:169], v[198:201], v[84:87]
	v_mfma_f32_16x16x32_bf16 v[80:83], v[174:177], v[198:201], v[80:83]
	v_mfma_f32_16x16x32_bf16 v[68:71], v[166:169], v[206:209], v[68:71]
	v_mfma_f32_16x16x32_bf16 v[64:67], v[174:177], v[206:209], v[64:67]
	v_mfma_f32_16x16x32_bf16 v[108:111], v[170:173], v[186:189], v[108:111]
	v_mfma_f32_16x16x32_bf16 v[104:107], v[178:181], v[186:189], v[104:107]
	v_mfma_f32_16x16x32_bf16 v[92:95], v[170:173], v[194:197], v[92:95]
	v_mfma_f32_16x16x32_bf16 v[88:91], v[178:181], v[194:197], v[88:91]
	v_mfma_f32_16x16x32_bf16 v[84:87], v[170:173], v[202:205], v[84:87]
	v_mfma_f32_16x16x32_bf16 v[80:83], v[178:181], v[202:205], v[80:83]
	v_mfma_f32_16x16x32_bf16 v[68:71], v[170:173], v[214:217], v[68:71]
	v_mfma_f32_16x16x32_bf16 v[64:67], v[178:181], v[214:217], v[64:67]
	s_setprio 0
	s_barrier
	s_add_i32 s68, s87, s3
	v_lshl_add_u64 v[210:211], v[210:211], 0, s[20:21]
	s_mov_b32 m0, s68
	ds_read_b128 v[182:185], v153 offset:49152
	ds_read_b128 v[186:189], v153 offset:50176
	ds_read_b128 v[190:193], v153 offset:51200
	ds_read_b128 v[194:197], v153 offset:52224
	ds_read_b128 v[198:201], v153 offset:53248
	ds_read_b128 v[202:205], v153 offset:54272
	ds_read_b128 v[206:209], v153 offset:55296
	ds_read_b128 v[214:217], v153 offset:56320
	global_load_lds_dwordx4 v[210:211], off
	s_add_i32 m0, s68, 0x2000
	s_add_u32 s66, s66, 0x80080
	v_lshl_add_u64 v[210:211], v[218:219], 0, s[20:21]
	s_addc_u32 s67, s67, 0
	s_add_i32 s68, s88, s3
	global_load_lds_dwordx4 v[210:211], off
	v_lshl_add_u64 v[210:211], s[66:67], 0, v[132:133]
	s_mov_b32 m0, s68
	s_nop 0
	global_load_lds_dwordx4 v[210:211], off
	v_lshl_add_u64 v[210:211], s[66:67], 0, v[128:129]
	s_add_i32 m0, s68, 0x2000
	s_nop 0
	global_load_lds_dwordx4 v[210:211], off
	v_lshl_add_u64 v[210:211], v[220:221], 0, s[20:21]
	s_mov_b32 m0, s74
	s_nop 0
	global_load_lds_dwordx4 v[210:211], off
	v_lshl_add_u64 v[210:211], v[222:223], 0, s[20:21]
	s_mov_b32 m0, s75
	s_nop 0
	global_load_lds_dwordx4 v[210:211], off
	s_waitcnt vmcnt(8)
	s_waitcnt lgkmcnt(0)
	v_mfma_f32_16x16x32_bf16 v[60:63], v[144:147], v[182:185], v[60:63]
	v_mfma_f32_16x16x32_bf16 v[56:59], v[158:161], v[182:185], v[56:59]
	s_barrier
	s_setprio 1
	s_waitcnt lgkmcnt(0)
	v_mfma_f32_16x16x32_bf16 v[52:55], v[144:147], v[190:193], v[52:55]
	v_mfma_f32_16x16x32_bf16 v[44:47], v[158:161], v[190:193], v[44:47]
	v_mfma_f32_16x16x32_bf16 v[36:39], v[144:147], v[198:201], v[36:39]
	v_mfma_f32_16x16x32_bf16 v[28:31], v[158:161], v[198:201], v[28:31]
	v_mfma_f32_16x16x32_bf16 v[20:23], v[144:147], v[206:209], v[20:23]
	v_mfma_f32_16x16x32_bf16 v[12:15], v[158:161], v[206:209], v[12:15]
	v_mfma_f32_16x16x32_bf16 v[60:63], v[154:157], v[186:189], v[60:63]
	v_mfma_f32_16x16x32_bf16 v[56:59], v[162:165], v[186:189], v[56:59]
	v_mfma_f32_16x16x32_bf16 v[52:55], v[154:157], v[194:197], v[52:55]
	v_mfma_f32_16x16x32_bf16 v[44:47], v[162:165], v[194:197], v[44:47]
	v_mfma_f32_16x16x32_bf16 v[36:39], v[154:157], v[202:205], v[36:39]
	v_mfma_f32_16x16x32_bf16 v[28:31], v[162:165], v[202:205], v[28:31]
	v_mfma_f32_16x16x32_bf16 v[20:23], v[154:157], v[214:217], v[20:23]
	v_mfma_f32_16x16x32_bf16 v[12:15], v[162:165], v[214:217], v[12:15]
	s_setprio 0
	s_setprio 1
	v_mfma_f32_16x16x32_bf16 v[48:51], v[166:169], v[182:185], v[48:51]
	v_mfma_f32_16x16x32_bf16 v[40:43], v[174:177], v[182:185], v[40:43]
	v_mfma_f32_16x16x32_bf16 v[32:35], v[166:169], v[190:193], v[32:35]
	v_mfma_f32_16x16x32_bf16 v[24:27], v[174:177], v[190:193], v[24:27]
	v_mfma_f32_16x16x32_bf16 v[16:19], v[166:169], v[198:201], v[16:19]
	v_mfma_f32_16x16x32_bf16 v[8:11], v[174:177], v[198:201], v[8:11]
	v_mfma_f32_16x16x32_bf16 v[4:7], v[166:169], v[206:209], v[4:7]
	v_mfma_f32_16x16x32_bf16 v[0:3], v[174:177], v[206:209], v[0:3]
	v_mfma_f32_16x16x32_bf16 v[48:51], v[170:173], v[186:189], v[48:51]
	v_mfma_f32_16x16x32_bf16 v[40:43], v[178:181], v[186:189], v[40:43]
	v_mfma_f32_16x16x32_bf16 v[32:35], v[170:173], v[194:197], v[32:35]
	v_mfma_f32_16x16x32_bf16 v[24:27], v[178:181], v[194:197], v[24:27]
	v_mfma_f32_16x16x32_bf16 v[16:19], v[170:173], v[202:205], v[16:19]
	v_mfma_f32_16x16x32_bf16 v[8:11], v[178:181], v[202:205], v[8:11]
	v_mfma_f32_16x16x32_bf16 v[4:7], v[170:173], v[214:217], v[4:7]
	v_mfma_f32_16x16x32_bf16 v[0:3], v[178:181], v[214:217], v[0:3]
	s_setprio 0
	s_barrier
	s_add_i32 s86, s86, 2
	s_add_u32 s64, s64, 0x100
	s_addc_u32 s65, s65, 0
	s_add_u32 s84, s84, 0x100
	s_addc_u32 s85, s85, 0
	s_cmp_gt_u32 s86, 29
	s_cbranch_scc0 .LBB0_115
	s_and_b64 vcc, exec, s[22:23]
	s_cbranch_vccz .LBB0_118
	s_barrier

.LBB0_247:
	s_waitcnt vmcnt(1)
	v_mul_f32_e32 v2, v101, v101
	v_pk_fma_f32 v[104:105], v[100:101], v[100:101], v[2:3] op_sel_hi:[1,1,0] neg_lo:[0,0,1] neg_hi:[0,0,1]
	v_pk_mul_f32 v[2:3], v[100:101], v[100:101] op_sel:[1,0] op_sel_hi:[0,1]
	v_pk_add_f32 v[106:107], v[2:3], v[2:3]
	s_mul_i32 s0, s35, 0x4200
	v_pk_mul_f32 v[2:3], v[100:101], v[106:107] op_sel:[1,0] op_sel_hi:[0,1]
	v_pk_fma_f32 v[108:109], v[100:101], v[104:105], v[2:3] neg_lo:[0,0,1] neg_hi:[0,0,1]
	v_pk_mul_f32 v[2:3], v[100:101], v[106:107]
	s_add_i32 s41, s0, 0
	v_pk_fma_f32 v[110:111], v[100:101], v[104:105], v[2:3] op_sel:[1,0,0] op_sel_hi:[0,1,1]
	v_pk_mul_f32 v[2:3], v[100:101], v[110:111] op_sel:[1,0] op_sel_hi:[0,1]
	v_pk_fma_f32 v[112:113], v[100:101], v[108:109], v[2:3] neg_lo:[0,0,1] neg_hi:[0,0,1]
	v_pk_mul_f32 v[2:3], v[100:101], v[110:111]
	s_lshr_b32 s0, s7, 6
	v_pk_fma_f32 v[114:115], v[100:101], v[108:109], v[2:3] op_sel:[1,0,0] op_sel_hi:[0,1,1]
	s_waitcnt vmcnt(0)
	v_mul_f32_e32 v2, v103, v103
	v_pk_fma_f32 v[116:117], v[102:103], v[102:103], v[2:3] op_sel_hi:[1,1,0] neg_lo:[0,0,1] neg_hi:[0,0,1]
	v_pk_mul_f32 v[2:3], v[102:103], v[102:103] op_sel:[1,0] op_sel_hi:[0,1]
	v_pk_add_f32 v[118:119], v[2:3], v[2:3]
	s_lshl_b32 s4, s6, 12
	v_pk_mul_f32 v[2:3], v[102:103], v[118:119] op_sel:[1,0] op_sel_hi:[0,1]
	v_pk_fma_f32 v[120:121], v[102:103], v[116:117], v[2:3] neg_lo:[0,0,1] neg_hi:[0,0,1]
	v_pk_mul_f32 v[2:3], v[102:103], v[118:119]
	v_and_b32_e32 v7, 15, v12
	v_pk_fma_f32 v[122:123], v[102:103], v[116:117], v[2:3] op_sel:[1,0,0] op_sel_hi:[0,1,1]
	v_pk_mul_f32 v[2:3], v[102:103], v[122:123] op_sel:[1,0] op_sel_hi:[0,1]
	s_add_u32 s4, s60, s4
	v_pk_fma_f32 v[124:125], v[102:103], v[120:121], v[2:3] neg_lo:[0,0,1] neg_hi:[0,0,1]
	v_pk_mul_f32 v[2:3], v[102:103], v[122:123]
	s_addc_u32 s5, s61, 0
	v_lshlrev_b32_e32 v128, 8, v7
	v_mov_b32_e32 v129, 0
	v_pk_fma_f32 v[126:127], v[102:103], v[120:121], v[2:3] op_sel:[1,0,0] op_sel_hi:[0,1,1]
	v_lshl_add_u64 v[2:3], s[4:5], 0, v[128:129]
	v_and_b32_e32 v128, 48, v13
	v_lshl_add_u64 v[2:3], v[2:3], 0, v[128:129]
	s_mov_b64 s[4:5], 0x6440000
	v_lshl_add_u64 v[4:5], v[2:3], 0, s[4:5]
	s_mov_b32 s4, 0x6440000
	v_add_co_u32_e32 v2, vcc, s4, v2
	s_add_u32 s4, s42, s20
	s_nop 0
	v_addc_co_u32_e32 v3, vcc, 0, v3, vcc
	global_load_dwordx4 v[80:83], v[4:5], off offset:64
	global_load_dwordx4 v[84:87], v[4:5], off offset:128
	global_load_dwordx4 v[88:91], v[2:3], off
	global_load_dwordx4 v[92:95], v[4:5], off offset:192
	s_addc_u32 s5, s43, 0
	global_load_dwordx4 v[96:99], v128, s[4:5]
	v_lshrrev_b32_e32 v111, 3, v13
	v_or_b32_e32 v123, 8, v111
	v_lshrrev_b32_e32 v20, 2, v123
	v_and_b32_e32 v9, 7, v12
	v_bitop3_b32 v20, v20, v12, 7 bitop3:0x78
	v_lshlrev_b32_e32 v130, 3, v9
	v_lshl_add_u32 v9, v9, 10, s41
	s_movk_i32 s6, 0x50
	s_movk_i32 s7, 0x60
	s_movk_i32 s20, 0x70
	v_lshlrev_b32_e32 v20, 4, v20
	v_or_b32_e32 v131, 16, v111
	v_add_u32_e32 v28, v9, v20
	v_xad_u32 v29, v20, 16, v9
	v_xad_u32 v30, v20, 32, v9
	v_xad_u32 v31, v20, 48, v9
	v_xad_u32 v32, v20, 64, v9
	v_xad_u32 v33, v20, s6, v9
	v_xad_u32 v34, v20, s7, v9
	v_xad_u32 v35, v20, s20, v9
	v_lshrrev_b32_e32 v20, 2, v131
	v_bitop3_b32 v20, v20, v12, 7 bitop3:0x78
	v_mbcnt_hi_u32_b32 v2, -1, v213
	v_lshlrev_b32_e32 v20, 4, v20
	v_or_b32_e32 v198, 24, v111
	v_and_b32_e32 v4, 64, v2
	v_add_u32_e32 v36, v9, v20
	v_xad_u32 v37, v20, 16, v9
	v_xad_u32 v38, v20, 32, v9
	v_xad_u32 v39, v20, 48, v9
	v_xad_u32 v40, v20, 64, v9
	v_xad_u32 v41, v20, s6, v9
	v_xad_u32 v42, v20, s7, v9
	v_xad_u32 v43, v20, s20, v9
	v_lshrrev_b32_e32 v20, 2, v198
	v_xor_b32_e32 v3, 32, v2
	v_add_u32_e32 v4, 64, v4
	v_cmp_gt_u32_e64 s[4:5], 32, v13
	v_lshrrev_b32_e32 v11, 1, v13
	v_bitop3_b32 v13, v1, v12, 7 bitop3:0x78
	v_bitop3_b32 v20, v20, v12, 7 bitop3:0x78
	v_cmp_lt_i32_e32 vcc, v3, v4
	v_lshlrev_b32_e32 v13, 4, v13
	v_lshlrev_b32_e32 v20, 4, v20
	s_lshl_b64 s[38:39], s[36:37], 13
	s_lshl_b32 s64, s40, 9
	v_cndmask_b32_e32 v2, v2, v3, vcc
	v_mov_b32_e32 v3, s41
	v_xad_u32 v26, v13, s6, v9
	v_xad_u32 v49, v20, s6, v9
	s_movk_i32 s6, 0x110
	v_mad_u32_u24 v199, v7, s6, v3
	s_add_u32 s6, s60, 0x4a00000
	v_xad_u32 v27, v13, s7, v9
	v_xad_u32 v50, v20, s7, v9
	s_addc_u32 s7, s61, 0
	v_add_u32_e32 v15, v9, v13
	v_xad_u32 v17, v13, 16, v9
	v_xad_u32 v19, v13, 32, v9
	v_xad_u32 v24, v13, 48, v9
	v_xad_u32 v25, v13, 64, v9
	v_xad_u32 v13, v13, s20, v9
	v_add_u32_e32 v44, v9, v20
	v_xad_u32 v45, v20, 16, v9
	v_xad_u32 v46, v20, 32, v9
	v_xad_u32 v47, v20, 48, v9
	v_xad_u32 v48, v20, 64, v9
	v_xad_u32 v9, v20, s20, v9
	s_add_u32 s20, s60, 0x1e00000
	s_addc_u32 s21, s61, 0
	s_add_u32 s24, s60, 0x1600000
	s_addc_u32 s25, s61, 0
	s_add_u32 s26, s60, 0x1400000
	s_addc_u32 s27, s61, 0
	s_lshl_b32 s42, s2, 8
	s_lshl_b32 s35, s35, 5
	s_add_i32 s35, s42, s35
	s_lshl_b64 s[42:43], s[36:37], 24
	s_lshl_b32 s37, s3, 14
	v_and_b32_e32 v119, 48, v12
	s_add_i32 s0, s34, s0
	s_and_b32 s37, s37, 0xf00000
	v_mul_u32_u24_e32 v51, 0x440, v1
	s_and_b32 s0, s0, 63
	s_or_b32 s37, s42, s37
	v_lshlrev_b32_e32 v1, 11, v7
	v_lshrrev_b32_e32 v52, 1, v119
	s_lshl_b32 s0, s0, 5
	v_or3_b32 v20, s37, v1, v52
	v_mov_b32_e32 v21, s43
	s_mul_hi_i32 s37, s36, 0x5000000
	s_mul_i32 s36, s36, 0x5000000
	s_mul_i32 s40, s40, 0x500000
	v_lshl_add_u64 v[20:21], s[60:61], 0, v[20:21]
	s_mov_b64 s[42:43], 0x1d208000
	s_add_u32 s36, s36, s40
	v_lshl_add_u64 v[156:157], v[20:21], 0, s[42:43]
	s_addc_u32 s37, s37, 0
	v_mul_hi_u32_u24_e32 v1, 0x2800, v7
	v_mul_u32_u24_e32 v20, 0x2800, v7
	v_or_b32_e32 v21, s37, v1
	v_or_b32_e32 v1, s36, v20
	v_or_b32_e32 v20, v1, v52
	v_lshl_add_u64 v[20:21], s[60:61], 0, v[20:21]
	s_mov_b64 s[36:37], 0xa62a000
	s_or_b32 s38, s38, s64
	v_lshl_add_u64 v[158:159], v[20:21], 0, s[36:37]
	v_or_b32_e32 v20, s38, v7
	v_mov_b32_e32 v21, s39
	v_lshlrev_b64 v[22:23], 11, v[20:21]
	v_or_b32_e32 v22, v22, v52
	v_lshl_add_u32 v5, v0, 3, s41
	s_movk_i32 s40, 0x2800
	v_lshl_add_u64 v[22:23], s[60:61], 0, v[22:23]
	s_mov_b64 s[36:37], 0x1d200000
	v_or_b32_e32 v0, s38, v0
	v_and_b32_e32 v7, 32, v12
	v_lshlrev_b32_e32 v107, 2, v2
	v_bitop3_b32 v2, v111, v12, 7 bitop3:0x78
	v_lshl_add_u64 v[160:161], v[22:23], 0, s[36:37]
	v_mad_u64_u32 v[20:21], s[36:37], v20, s40, 0
	s_mul_i32 s42, s39, 0x2800
	v_mad_u64_u32 v[0:1], s[38:39], v0, s40, 0
	v_lshrrev_b32_e32 v7, 1, v7
	v_lshlrev_b32_e32 v2, 2, v2
	v_add_u32_e32 v21, s42, v21
	v_or_b32_e32 v20, v20, v52
	v_add_u32_e32 v1, s42, v1
	v_or_b32_e32 v0, v0, v7
	s_mov_b32 s1, 0
	v_xor_b32_e32 v4, 4, v2
	v_xor_b32_e32 v6, 8, v2
	v_xor_b32_e32 v8, 12, v2
	v_xor_b32_e32 v10, 16, v2
	v_xor_b32_e32 v14, 20, v2
	v_xor_b32_e32 v16, 24, v2
	v_xor_b32_e32 v18, 28, v2
	v_and_b32_e32 v11, 12, v11
	v_xor_b32_e32 v133, 0x80000000, v101
	v_xor_b32_e32 v135, 0x80000000, v103
	v_xor_b32_e32 v115, 0x80000000, v114
	v_xor_b32_e32 v127, 0x80000000, v126
	v_add_u32_e32 v3, 0x1100, v199
	v_lshl_add_u64 v[20:21], s[60:61], 0, v[20:21]
	s_mov_b64 s[36:37], 0xa602000
	v_lshl_add_u64 v[0:1], s[60:61], 0, v[0:1]
	v_xor_b32_e32 v136, 0x80000000, v106
	v_xor_b32_e32 v138, 0x80000000, v118
	v_xor_b32_e32 v140, 0x80000000, v110
	v_xor_b32_e32 v142, 0x80000000, v122
	v_mov_b32_e32 v144, v102
	v_mov_b32_e32 v145, v102
	v_mov_b32_e32 v125, v124
	v_mov_b32_e32 v134, v103
	v_mov_b32_e32 v146, v100
	v_mov_b32_e32 v147, v100
	v_mov_b32_e32 v113, v112
	v_mov_b32_e32 v132, v101
	v_mov_b32_e32 v148, v135
	v_mov_b32_e32 v149, v103
	v_mov_b32_e32 v150, v133
	v_mov_b32_e32 v151, v101
	v_mov_b32_e32 v117, v116
	v_mov_b32_e32 v139, v118
	v_mov_b32_e32 v105, v104
	v_mov_b32_e32 v137, v106
	v_mov_b32_e32 v121, v120
	v_mov_b32_e32 v143, v122
	v_mov_b32_e32 v109, v108
	v_mov_b32_e32 v141, v110
	v_mov_b32_e32 v152, v127
	v_mov_b32_e32 v153, v126
	v_mov_b32_e32 v154, v115
	v_mov_b32_e32 v155, v114
	v_lshl_add_u64 v[162:163], v[20:21], 0, s[36:37]
	v_lshl_add_u64 v[164:165], v[0:1], 0, s[36:37]
	v_lshlrev_b32_e32 v166, 2, v2
	s_add_i32 s74, s41, 0x2200
	v_lshlrev_b32_e32 v168, 2, v4
	s_add_i32 s75, s41, 0x2600
	v_lshlrev_b32_e32 v170, 2, v6
	s_add_i32 s76, s41, 0x2a00
	v_lshlrev_b32_e32 v172, 2, v8
	s_add_i32 s77, s41, 0x2e00
	v_lshlrev_b32_e32 v174, 2, v10
	s_add_i32 s78, s41, 0x3200
	v_lshlrev_b32_e32 v176, 2, v14
	s_add_i32 s79, s41, 0x3600
	v_lshlrev_b32_e32 v178, 2, v16
	s_add_i32 s80, s41, 0x3a00
	v_lshlrev_b32_e32 v180, 2, v18
	s_add_i32 s81, s41, 0x3e00
	v_add_u32_e32 v200, v5, v51
	v_add_u32_e32 v201, v3, v119
	v_add_u32_e32 v202, v15, v11
	v_add_u32_e32 v203, v17, v11
	v_add_u32_e32 v204, v19, v11
	v_add_u32_e32 v205, v24, v11
	v_add_u32_e32 v206, v25, v11
	v_add_u32_e32 v207, v26, v11
	v_add_u32_e32 v208, v27, v11
	v_add_u32_e32 v209, v13, v11
	v_add_u32_e32 v210, v28, v11
	v_add_u32_e32 v211, v29, v11
	v_add_u32_e32 v214, v30, v11
	v_add_u32_e32 v215, v31, v11
	v_add_u32_e32 v216, v32, v11
	v_add_u32_e32 v217, v33, v11
	v_add_u32_e32 v218, v34, v11
	v_add_u32_e32 v219, v35, v11
	v_add_u32_e32 v220, v36, v11
	v_add_u32_e32 v221, v37, v11
	v_add_u32_e32 v222, v38, v11
	v_add_u32_e32 v223, v39, v11
	v_add_u32_e32 v224, v40, v11
	v_add_u32_e32 v225, v41, v11
	v_add_u32_e32 v226, v42, v11
	v_add_u32_e32 v227, v43, v11
	v_add_u32_e32 v228, v44, v11
	v_add_u32_e32 v229, v45, v11
	v_add_u32_e32 v230, v46, v11
	v_add_u32_e32 v231, v47, v11
	v_add_u32_e32 v232, v48, v11
	v_add_u32_e32 v233, v49, v11
	v_add_u32_e32 v234, v50, v11
	v_add_u32_e32 v235, v9, v11
	s_mov_b64 s[36:37], 0x10000
	s_mov_b64 s[38:39], 0x50000
	s_mov_b32 s82, s1
	s_mov_b32 s83, s1
	v_lshl_add_u64 v[250:251], v[164:165], 0, s[0:1]
	global_load_dwordx4 v[246:249], v[250:251], off
	s_branch .LBB0_251

.LBB0_251:
	s_cmp_gt_u32 s83, 9
	s_waitcnt vmcnt(0)
	v_mfma_f32_32x32x16_bf16 v[48:63], v[246:249], v[64:67], 0
	v_mfma_f32_32x32x16_bf16 v[0:15], v[246:249], v[68:71], 0
	v_mfma_f32_32x32x16_bf16 v[32:47], v[246:249], v[72:75], 0
	v_mfma_f32_32x32x16_bf16 v[16:31], v[246:249], v[76:79], 0
	v_lshl_add_u64 v[250:251], v[164:165], 0, s[38:39]
	v_lshl_add_u64 v[250:251], v[250:251], 0, s[0:1]
	global_load_dwordx4 v[246:249], v[250:251], off
	s_cbranch_scc1 .LBB0_259
	s_add_i32 s65, s3, s82
	s_cmpk_lt_u32 s65, 0x4c00
	s_cselect_b64 s[72:73], -1, 0
	s_cmpk_gt_u32 s65, 0x4bff
	s_mov_b64 s[42:43], 0
	s_cbranch_scc1 .LBB0_269
	s_cmpk_gt_u32 s65, 0x1ff
	s_cbranch_scc0 .LBB0_260
	s_cmpk_gt_u32 s65, 0x9ff
	s_cbranch_scc0 .LBB0_261
	s_cmpk_gt_u32 s65, 0x1fff
	s_cbranch_scc0 .LBB0_262
	s_cmpk_gt_u32 s65, 0x35ff
	s_cbranch_scc0 .LBB0_274
	s_add_i32 s40, s65, 0xffffca00
	s_lshr_b32 s86, s40, 6
	s_and_b32 s64, s35, 0x7e0
	s_mov_b64 s[40:41], s[58:59]
	s_cbranch_execz .LBB0_275
	s_movk_i32 s66, 0x800
	s_movk_i32 s84, 0x1600
	s_mov_b64 s[68:69], s[6:7]
	s_mov_b32 s85, s64
	s_cbranch_execz .LBB0_263
	s_branch .LBB0_264

.LBB0_349:
	ds_read_b128 v[56:59], v217
	ds_read_b128 v[60:63], v217 offset:1024
	ds_read_b128 v[64:67], v217 offset:2048
	ds_read_b128 v[68:71], v217 offset:3072
	ds_read_b128 v[72:75], v218
	ds_read_b128 v[76:79], v218 offset:1024
	ds_read_b128 v[80:83], v218 offset:2048
	ds_read_b128 v[84:87], v218 offset:3072
	s_add_u32 s54, s52, 0xfffc0080
	s_addc_u32 s55, s53, -1
	s_cmp_eq_u32 s80, 12
	s_cselect_b32 s57, s41, s55
	s_cselect_b32 s56, s51, s54
	s_cselect_b32 s55, s39, s79
	s_cselect_b32 s54, s77, s78
	v_lshl_add_u64 v[208:209], s[52:53], 0, v[192:193]
	s_add_i32 m0, s64, 0xc000
	ds_read_b128 v[144:147], v219
	ds_read_b128 v[156:159], v219 offset:1024
	ds_read_b128 v[168:171], v219 offset:2048
	ds_read_b128 v[172:175], v219 offset:3072
	ds_read_b128 v[176:179], v219 offset:4096
	ds_read_b128 v[180:183], v219 offset:5120
	ds_read_b128 v[200:203], v219 offset:6144
	ds_read_b128 v[204:207], v219 offset:7168
	global_load_lds_dwordx4 v[208:209], off
	v_lshl_add_u64 v[208:209], s[52:53], 0, v[194:195]
	s_add_i32 m0, s64, 0xe000
	s_nop 0
	global_load_lds_dwordx4 v[208:209], off
	s_waitcnt vmcnt(8)
	s_waitcnt lgkmcnt(0)
	v_mfma_f32_16x16x32_bf16 v[164:167], v[56:59], v[144:147], v[164:167]
	v_mfma_f32_16x16x32_bf16 v[160:163], v[64:67], v[144:147], v[160:163]
	s_barrier
	s_setprio 1
	s_waitcnt lgkmcnt(0)
	v_mfma_f32_16x16x32_bf16 v[140:143], v[56:59], v[168:171], v[140:143]
	v_mfma_f32_16x16x32_bf16 v[136:139], v[64:67], v[168:171], v[136:139]
	v_mfma_f32_16x16x32_bf16 v[124:127], v[56:59], v[176:179], v[124:127]
	v_mfma_f32_16x16x32_bf16 v[120:123], v[64:67], v[176:179], v[120:123]
	v_mfma_f32_16x16x32_bf16 v[108:111], v[56:59], v[200:203], v[108:111]
	v_mfma_f32_16x16x32_bf16 v[104:107], v[64:67], v[200:203], v[104:107]
	v_mfma_f32_16x16x32_bf16 v[164:167], v[60:63], v[156:159], v[164:167]
	v_mfma_f32_16x16x32_bf16 v[160:163], v[68:71], v[156:159], v[160:163]
	v_mfma_f32_16x16x32_bf16 v[140:143], v[60:63], v[172:175], v[140:143]
	v_mfma_f32_16x16x32_bf16 v[136:139], v[68:71], v[172:175], v[136:139]
	v_mfma_f32_16x16x32_bf16 v[124:127], v[60:63], v[180:183], v[124:127]
	v_mfma_f32_16x16x32_bf16 v[120:123], v[68:71], v[180:183], v[120:123]
	v_mfma_f32_16x16x32_bf16 v[108:111], v[60:63], v[204:207], v[108:111]
	v_mfma_f32_16x16x32_bf16 v[104:107], v[68:71], v[204:207], v[104:107]
	s_setprio 0
	s_setprio 1
	v_mfma_f32_16x16x32_bf16 v[152:155], v[72:75], v[144:147], v[152:155]
	v_mfma_f32_16x16x32_bf16 v[132:135], v[72:75], v[168:171], v[132:135]
	v_mfma_f32_16x16x32_bf16 v[128:131], v[80:83], v[168:171], v[128:131]
	v_mfma_f32_16x16x32_bf16 v[116:119], v[72:75], v[176:179], v[116:119]
	v_mfma_f32_16x16x32_bf16 v[112:115], v[80:83], v[176:179], v[112:115]
	v_mfma_f32_16x16x32_bf16 v[100:103], v[72:75], v[200:203], v[100:103]
	v_mfma_f32_16x16x32_bf16 v[96:99], v[80:83], v[200:203], v[96:99]
	v_mfma_f32_16x16x32_bf16 v[152:155], v[76:79], v[156:159], v[152:155]
	v_mfma_f32_16x16x32_bf16 v[144:147], v[80:83], v[144:147], v[148:151]
	v_mfma_f32_16x16x32_bf16 v[132:135], v[76:79], v[172:175], v[132:135]
	v_mfma_f32_16x16x32_bf16 v[128:131], v[84:87], v[172:175], v[128:131]
	v_mfma_f32_16x16x32_bf16 v[116:119], v[76:79], v[180:183], v[116:119]
	v_mfma_f32_16x16x32_bf16 v[112:115], v[84:87], v[180:183], v[112:115]
	v_mfma_f32_16x16x32_bf16 v[100:103], v[76:79], v[204:207], v[100:103]
	v_mfma_f32_16x16x32_bf16 v[96:99], v[84:87], v[204:207], v[96:99]
	v_mfma_f32_16x16x32_bf16 v[144:147], v[84:87], v[156:159], v[144:147]
	s_setprio 0
	s_barrier
	s_add_i32 s81, s74, s59
	v_lshl_add_u64 v[208:209], s[54:55], 0, v[186:187]
	s_mov_b32 m0, s81
	ds_read_b128 v[148:151], v219 offset:16384
	ds_read_b128 v[156:159], v219 offset:17408
	ds_read_b128 v[168:171], v219 offset:18432
	ds_read_b128 v[172:175], v219 offset:19456
	ds_read_b128 v[176:179], v219 offset:20480
	ds_read_b128 v[180:183], v219 offset:21504
	ds_read_b128 v[200:203], v219 offset:22528
	ds_read_b128 v[204:207], v219 offset:23552
	global_load_lds_dwordx4 v[208:209], off
	s_add_i32 m0, s81, 0x2000
	s_add_u32 s82, s54, 0x40000
	v_lshl_add_u64 v[210:211], s[54:55], 0, v[190:191]
	s_addc_u32 s83, s55, 0
	s_add_i32 s81, s75, s59
	global_load_lds_dwordx4 v[210:211], off
	v_lshl_add_u64 v[222:223], s[82:83], 0, v[186:187]
	s_mov_b32 m0, s81
	v_lshl_add_u64 v[224:225], s[56:57], 0, v[188:189]
	global_load_lds_dwordx4 v[222:223], off
	v_lshl_add_u64 v[222:223], s[82:83], 0, v[190:191]
	s_add_i32 m0, s81, 0x2000
	s_nop 0
	global_load_lds_dwordx4 v[222:223], off
	v_lshl_add_u64 v[222:223], s[56:57], 0, v[184:185]
	s_mov_b32 m0, s64
	s_nop 0
	global_load_lds_dwordx4 v[222:223], off
	s_mov_b32 m0, s65
	s_nop 0
	global_load_lds_dwordx4 v[224:225], off
	s_waitcnt vmcnt(8)
	s_waitcnt lgkmcnt(0)
	v_mfma_f32_16x16x32_bf16 v[92:95], v[56:59], v[148:151], v[92:95]
	v_mfma_f32_16x16x32_bf16 v[88:91], v[64:67], v[148:151], v[88:91]
	s_barrier
	s_setprio 1
	s_waitcnt lgkmcnt(0)
	v_mfma_f32_16x16x32_bf16 v[44:47], v[56:59], v[168:171], v[44:47]
	v_mfma_f32_16x16x32_bf16 v[40:43], v[64:67], v[168:171], v[40:43]
	v_mfma_f32_16x16x32_bf16 v[28:31], v[56:59], v[176:179], v[28:31]
	v_mfma_f32_16x16x32_bf16 v[24:27], v[64:67], v[176:179], v[24:27]
	v_mfma_f32_16x16x32_bf16 v[12:15], v[56:59], v[200:203], v[12:15]
	v_mfma_f32_16x16x32_bf16 v[8:11], v[64:67], v[200:203], v[8:11]
	v_mfma_f32_16x16x32_bf16 v[92:95], v[60:63], v[156:159], v[92:95]
	v_mfma_f32_16x16x32_bf16 v[88:91], v[68:71], v[156:159], v[88:91]
	v_mfma_f32_16x16x32_bf16 v[44:47], v[60:63], v[172:175], v[44:47]
	v_mfma_f32_16x16x32_bf16 v[40:43], v[68:71], v[172:175], v[40:43]
	v_mfma_f32_16x16x32_bf16 v[28:31], v[60:63], v[180:183], v[28:31]
	v_mfma_f32_16x16x32_bf16 v[24:27], v[68:71], v[180:183], v[24:27]
	v_mfma_f32_16x16x32_bf16 v[12:15], v[60:63], v[204:207], v[12:15]
	v_mfma_f32_16x16x32_bf16 v[8:11], v[68:71], v[204:207], v[8:11]
	s_setprio 0
	s_setprio 1
	v_mfma_f32_16x16x32_bf16 v[52:55], v[72:75], v[148:151], v[52:55]
	v_mfma_f32_16x16x32_bf16 v[48:51], v[80:83], v[148:151], v[48:51]
	v_mfma_f32_16x16x32_bf16 v[36:39], v[72:75], v[168:171], v[36:39]
	v_mfma_f32_16x16x32_bf16 v[32:35], v[80:83], v[168:171], v[32:35]
	v_mfma_f32_16x16x32_bf16 v[20:23], v[72:75], v[176:179], v[20:23]
	v_mfma_f32_16x16x32_bf16 v[16:19], v[80:83], v[176:179], v[16:19]
	v_mfma_f32_16x16x32_bf16 v[4:7], v[72:75], v[200:203], v[4:7]
	v_mfma_f32_16x16x32_bf16 v[0:3], v[80:83], v[200:203], v[0:3]
	v_mfma_f32_16x16x32_bf16 v[52:55], v[76:79], v[156:159], v[52:55]
	v_mfma_f32_16x16x32_bf16 v[48:51], v[84:87], v[156:159], v[48:51]
	v_mfma_f32_16x16x32_bf16 v[36:39], v[76:79], v[172:175], v[36:39]
	v_mfma_f32_16x16x32_bf16 v[32:35], v[84:87], v[172:175], v[32:35]
	v_mfma_f32_16x16x32_bf16 v[20:23], v[76:79], v[180:183], v[20:23]
	v_mfma_f32_16x16x32_bf16 v[16:19], v[84:87], v[180:183], v[16:19]
	v_mfma_f32_16x16x32_bf16 v[4:7], v[76:79], v[204:207], v[4:7]
	v_mfma_f32_16x16x32_bf16 v[0:3], v[84:87], v[204:207], v[0:3]
	s_setprio 0
	s_barrier
	s_add_i32 s81, 0, 0x18000
	s_add_i32 s82, 0, 0x1c000
	v_add_u32_e32 v68, s81, v215
	v_add_u32_e32 v84, s82, v215
	ds_read_b128 v[56:59], v68
	ds_read_b128 v[60:63], v68 offset:1024
	ds_read_b128 v[64:67], v68 offset:2048
	ds_read_b128 v[68:71], v68 offset:3072
	ds_read_b128 v[72:75], v84
	ds_read_b128 v[76:79], v84 offset:1024
	ds_read_b128 v[80:83], v84 offset:2048
	ds_read_b128 v[84:87], v84 offset:3072
	s_add_u32 s56, s56, 0x40000
	s_addc_u32 s57, s57, 0
	s_mov_b32 m0, s66
	v_lshl_add_u64 v[226:227], s[56:57], 0, v[184:185]
	ds_read_b128 v[148:151], v219 offset:32768
	ds_read_b128 v[156:159], v219 offset:33792
	ds_read_b128 v[168:171], v219 offset:34816
	ds_read_b128 v[172:175], v219 offset:35840
	ds_read_b128 v[176:179], v219 offset:36864
	ds_read_b128 v[180:183], v219 offset:37888
	ds_read_b128 v[200:203], v219 offset:38912
	ds_read_b128 v[204:207], v219 offset:39936
	global_load_lds_dwordx4 v[226:227], off
	v_lshl_add_u64 v[226:227], s[56:57], 0, v[188:189]
	s_mov_b32 m0, s67
	s_nop 0
	global_load_lds_dwordx4 v[226:227], off
	s_waitcnt vmcnt(8)
	s_waitcnt lgkmcnt(0)
	v_mfma_f32_16x16x32_bf16 v[164:167], v[56:59], v[148:151], v[164:167]
	v_mfma_f32_16x16x32_bf16 v[160:163], v[64:67], v[148:151], v[160:163]
	s_barrier
	s_setprio 1
	s_waitcnt lgkmcnt(0)
	v_mfma_f32_16x16x32_bf16 v[140:143], v[56:59], v[168:171], v[140:143]
	v_mfma_f32_16x16x32_bf16 v[136:139], v[64:67], v[168:171], v[136:139]
	v_mfma_f32_16x16x32_bf16 v[124:127], v[56:59], v[176:179], v[124:127]
	v_mfma_f32_16x16x32_bf16 v[120:123], v[64:67], v[176:179], v[120:123]
	v_mfma_f32_16x16x32_bf16 v[108:111], v[56:59], v[200:203], v[108:111]
	v_mfma_f32_16x16x32_bf16 v[104:107], v[64:67], v[200:203], v[104:107]
	v_mfma_f32_16x16x32_bf16 v[164:167], v[60:63], v[156:159], v[164:167]
	v_mfma_f32_16x16x32_bf16 v[160:163], v[68:71], v[156:159], v[160:163]
	v_mfma_f32_16x16x32_bf16 v[140:143], v[60:63], v[172:175], v[140:143]
	v_mfma_f32_16x16x32_bf16 v[136:139], v[68:71], v[172:175], v[136:139]
	v_mfma_f32_16x16x32_bf16 v[124:127], v[60:63], v[180:183], v[124:127]
	v_mfma_f32_16x16x32_bf16 v[120:123], v[68:71], v[180:183], v[120:123]
	v_mfma_f32_16x16x32_bf16 v[108:111], v[60:63], v[204:207], v[108:111]
	v_mfma_f32_16x16x32_bf16 v[104:107], v[68:71], v[204:207], v[104:107]
	s_setprio 0
	s_setprio 1
	v_mfma_f32_16x16x32_bf16 v[152:155], v[72:75], v[148:151], v[152:155]
	v_mfma_f32_16x16x32_bf16 v[144:147], v[80:83], v[148:151], v[144:147]
	v_mfma_f32_16x16x32_bf16 v[132:135], v[72:75], v[168:171], v[132:135]
	v_mfma_f32_16x16x32_bf16 v[128:131], v[80:83], v[168:171], v[128:131]
	v_mfma_f32_16x16x32_bf16 v[116:119], v[72:75], v[176:179], v[116:119]
	v_mfma_f32_16x16x32_bf16 v[112:115], v[80:83], v[176:179], v[112:115]
	v_mfma_f32_16x16x32_bf16 v[100:103], v[72:75], v[200:203], v[100:103]
	v_mfma_f32_16x16x32_bf16 v[96:99], v[80:83], v[200:203], v[96:99]
	v_mfma_f32_16x16x32_bf16 v[152:155], v[76:79], v[156:159], v[152:155]
	v_mfma_f32_16x16x32_bf16 v[148:151], v[84:87], v[156:159], v[144:147]
	v_mfma_f32_16x16x32_bf16 v[132:135], v[76:79], v[172:175], v[132:135]
	v_mfma_f32_16x16x32_bf16 v[128:131], v[84:87], v[172:175], v[128:131]
	v_mfma_f32_16x16x32_bf16 v[116:119], v[76:79], v[180:183], v[116:119]
	v_mfma_f32_16x16x32_bf16 v[112:115], v[84:87], v[180:183], v[112:115]
	v_mfma_f32_16x16x32_bf16 v[100:103], v[76:79], v[204:207], v[100:103]
	v_mfma_f32_16x16x32_bf16 v[96:99], v[84:87], v[204:207], v[96:99]
	s_setprio 0
	s_barrier
	s_add_i32 s56, s81, s59
	v_lshl_add_u64 v[208:209], v[208:209], 0, s[36:37]
	s_mov_b32 m0, s56
	ds_read_b128 v[144:147], v219 offset:49152
	ds_read_b128 v[156:159], v219 offset:50176
	ds_read_b128 v[168:171], v219 offset:51200
	ds_read_b128 v[172:175], v219 offset:52224
	ds_read_b128 v[176:179], v219 offset:53248
	ds_read_b128 v[180:183], v219 offset:54272
	ds_read_b128 v[200:203], v219 offset:55296
	ds_read_b128 v[204:207], v219 offset:56320
	global_load_lds_dwordx4 v[208:209], off
	s_add_i32 m0, s56, 0x2000
	s_add_u32 s54, s54, 0x40080
	v_lshl_add_u64 v[208:209], v[210:211], 0, s[36:37]
	s_addc_u32 s55, s55, 0
	s_add_i32 s56, s82, s59
	global_load_lds_dwordx4 v[208:209], off
	v_lshl_add_u64 v[208:209], s[54:55], 0, v[186:187]
	s_mov_b32 m0, s56
	s_nop 0
	global_load_lds_dwordx4 v[208:209], off
	v_lshl_add_u64 v[208:209], s[54:55], 0, v[190:191]
	s_add_i32 m0, s56, 0x2000
	s_nop 0
	global_load_lds_dwordx4 v[208:209], off
	v_lshl_add_u64 v[208:209], v[222:223], 0, s[36:37]
	s_mov_b32 m0, s69
	s_nop 0
	global_load_lds_dwordx4 v[208:209], off
	v_lshl_add_u64 v[208:209], v[224:225], 0, s[36:37]
	s_mov_b32 m0, s70
	s_nop 0
	global_load_lds_dwordx4 v[208:209], off
	s_waitcnt vmcnt(8)
	s_waitcnt lgkmcnt(0)
	v_mfma_f32_16x16x32_bf16 v[92:95], v[56:59], v[144:147], v[92:95]
	v_mfma_f32_16x16x32_bf16 v[88:91], v[64:67], v[144:147], v[88:91]
	s_barrier
	s_setprio 1
	s_waitcnt lgkmcnt(0)
	v_mfma_f32_16x16x32_bf16 v[44:47], v[56:59], v[168:171], v[44:47]
	v_mfma_f32_16x16x32_bf16 v[40:43], v[64:67], v[168:171], v[40:43]
	v_mfma_f32_16x16x32_bf16 v[28:31], v[56:59], v[176:179], v[28:31]
	v_mfma_f32_16x16x32_bf16 v[24:27], v[64:67], v[176:179], v[24:27]
	v_mfma_f32_16x16x32_bf16 v[12:15], v[56:59], v[200:203], v[12:15]
	v_mfma_f32_16x16x32_bf16 v[8:11], v[64:67], v[200:203], v[8:11]
	v_mfma_f32_16x16x32_bf16 v[92:95], v[60:63], v[156:159], v[92:95]
	v_mfma_f32_16x16x32_bf16 v[88:91], v[68:71], v[156:159], v[88:91]
	v_mfma_f32_16x16x32_bf16 v[44:47], v[60:63], v[172:175], v[44:47]
	v_mfma_f32_16x16x32_bf16 v[40:43], v[68:71], v[172:175], v[40:43]
	v_mfma_f32_16x16x32_bf16 v[28:31], v[60:63], v[180:183], v[28:31]
	v_mfma_f32_16x16x32_bf16 v[24:27], v[68:71], v[180:183], v[24:27]
	v_mfma_f32_16x16x32_bf16 v[12:15], v[60:63], v[204:207], v[12:15]
	v_mfma_f32_16x16x32_bf16 v[8:11], v[68:71], v[204:207], v[8:11]
	s_setprio 0
	s_setprio 1
	v_mfma_f32_16x16x32_bf16 v[52:55], v[72:75], v[144:147], v[52:55]
	v_mfma_f32_16x16x32_bf16 v[48:51], v[80:83], v[144:147], v[48:51]
	v_mfma_f32_16x16x32_bf16 v[36:39], v[72:75], v[168:171], v[36:39]
	v_mfma_f32_16x16x32_bf16 v[32:35], v[80:83], v[168:171], v[32:35]
	v_mfma_f32_16x16x32_bf16 v[20:23], v[72:75], v[176:179], v[20:23]
	v_mfma_f32_16x16x32_bf16 v[16:19], v[80:83], v[176:179], v[16:19]
	v_mfma_f32_16x16x32_bf16 v[4:7], v[72:75], v[200:203], v[4:7]
	v_mfma_f32_16x16x32_bf16 v[0:3], v[80:83], v[200:203], v[0:3]
	v_mfma_f32_16x16x32_bf16 v[52:55], v[76:79], v[156:159], v[52:55]
	v_mfma_f32_16x16x32_bf16 v[48:51], v[84:87], v[156:159], v[48:51]
	v_mfma_f32_16x16x32_bf16 v[36:39], v[76:79], v[172:175], v[36:39]
	v_mfma_f32_16x16x32_bf16 v[32:35], v[84:87], v[172:175], v[32:35]
	v_mfma_f32_16x16x32_bf16 v[20:23], v[76:79], v[180:183], v[20:23]
	v_mfma_f32_16x16x32_bf16 v[16:19], v[84:87], v[180:183], v[16:19]
	v_mfma_f32_16x16x32_bf16 v[4:7], v[76:79], v[204:207], v[4:7]
	v_mfma_f32_16x16x32_bf16 v[0:3], v[84:87], v[204:207], v[0:3]
	s_setprio 0
	s_barrier
	s_add_i32 s80, s80, 2
	s_add_u32 s52, s52, 0x100
	s_addc_u32 s53, s53, 0
	s_add_u32 s78, s78, 0x100
	s_addc_u32 s79, s79, 0
	s_cmp_gt_u32 s80, 13
	s_cbranch_scc0 .LBB0_349
	v_lshl_or_b32 v200, s20, 8, v216
	v_ashrrev_i32_e32 v201, 31, v200
	v_lshl_add_u32 v204, s50, 8, v214
	v_lshlrev_b64 v[56:57], 2, v[200:201]
	v_lshlrev_b64 v[232:233], 1, v[200:201]
	v_ashrrev_i32_e32 v205, 31, v204
	v_lshl_add_u64 v[58:59], s[46:47], 0, v[56:57]
	v_lshl_add_u64 v[202:203], s[0:1], 0, v[232:233]
	v_lshlrev_b64 v[60:61], 11, v[204:205]
	global_load_dwordx4 v[80:83], v[58:59], off offset:16
	global_load_dwordx4 v[84:87], v[58:59], off
	v_lshl_add_u64 v[144:145], v[202:203], 0, v[60:61]
	global_load_dwordx4 v[224:227], v[144:145], off
	v_and_b32_e32 v60, 64, v220
	v_xor_b32_e32 v62, 16, v220
	v_add_u32_e32 v64, 64, v60
	v_xor_b32_e32 v63, 32, v220
	v_lshl_add_u64 v[60:61], s[48:49], 0, v[56:57]
	v_cmp_lt_i32_e32 vcc, v62, v64
	global_load_dwordx4 v[68:71], v[60:61], off offset:16
	global_load_dwordx4 v[72:75], v[60:61], off
	v_cndmask_b32_e32 v56, v220, v62, vcc
	v_cmp_lt_i32_e32 vcc, v63, v64
	global_load_dwordx4 v[64:67], v[58:59], off offset:528
	global_load_dwordx4 v[76:79], v[58:59], off offset:512
	v_or_b32_e32 v210, 16, v204
	v_or_b32_e32 v208, 32, v204
	v_or_b32_e32 v206, 48, v204
	v_ashrrev_i32_e32 v211, 31, v210
	v_ashrrev_i32_e32 v209, 31, v208
	v_ashrrev_i32_e32 v207, 31, v206
	v_lshlrev_b64 v[146:147], 11, v[210:211]
	v_lshlrev_b64 v[156:157], 11, v[208:209]
	v_cndmask_b32_e32 v57, v220, v63, vcc
	v_lshlrev_b64 v[158:159], 11, v[206:207]
	v_lshl_add_u64 v[146:147], v[202:203], 0, v[146:147]
	v_lshl_add_u64 v[156:157], v[202:203], 0, v[156:157]
	v_lshlrev_b32_e32 v222, 2, v56
	v_lshlrev_b32_e32 v221, 2, v57
	global_load_dwordx4 v[56:59], v[60:61], off offset:528
	s_nop 0
	global_load_dwordx4 v[60:63], v[60:61], off offset:512
	v_lshl_add_u64 v[234:235], v[202:203], 0, v[158:159]
	global_load_dwordx4 v[228:231], v[144:145], off offset:256
	global_load_dwordx4 v[180:183], v[146:147], off
	global_load_dwordx4 v[176:179], v[146:147], off offset:256
	global_load_dwordx4 v[172:175], v[156:157], off
	global_load_dwordx4 v[168:171], v[156:157], off offset:256
	s_nop 0
	global_load_dwordx4 v[156:159], v[234:235], off
	global_load_dwordx4 v[144:147], v[234:235], off offset:256
	s_lshl_b32 s50, s20, 2
	s_ashr_i32 s51, s50, 31
	s_waitcnt vmcnt(0)
	v_pk_add_f32 v[162:163], v[162:163], v[82:83]
	v_pk_add_f32 v[166:167], v[166:167], v[86:87]
	v_pk_add_f32 v[164:165], v[164:165], v[84:85]
	v_pk_add_f32 v[160:161], v[160:161], v[80:81]
	v_mul_f32_e32 v223, 0xbfb8aa3b, v164
	v_mul_f32_e32 v234, 0xbfb8aa3b, v165
	v_lshlrev_b32_e32 v164, 16, v224
	v_and_b32_e32 v165, 0xffff0000, v224
	v_mul_f32_e32 v224, 0xbfb8aa3b, v166
	v_mul_f32_e32 v235, 0xbfb8aa3b, v167
	v_lshlrev_b32_e32 v166, 16, v225
	v_and_b32_e32 v167, 0xffff0000, v225
	v_mul_f32_e32 v225, 0xbfb8aa3b, v160
	v_mul_f32_e32 v236, 0xbfb8aa3b, v161
	v_lshlrev_b32_e32 v160, 16, v226
	v_and_b32_e32 v161, 0xffff0000, v226
	v_mul_f32_e32 v162, 0xbfb8aa3b, v162
	v_mul_f32_e32 v163, 0xbfb8aa3b, v163
	v_exp_f32_e32 v223, v223
	v_exp_f32_e32 v226, v234
	v_exp_f32_e32 v224, v224
	v_exp_f32_e32 v234, v235
	v_exp_f32_e32 v225, v225
	v_exp_f32_e32 v235, v236
	v_exp_f32_e32 v162, v162
	v_exp_f32_e32 v163, v163
	v_add_f32_e32 v223, 1.0, v223
	v_add_f32_e32 v226, 1.0, v226
	v_add_f32_e32 v224, 1.0, v224
	v_add_f32_e32 v234, 1.0, v234
	v_add_f32_e32 v236, 1.0, v225
	v_add_f32_e32 v235, 1.0, v235
	v_add_f32_e32 v237, 1.0, v162
	v_add_f32_e32 v238, 1.0, v163
	v_rcp_f32_e32 v162, v223
	v_rcp_f32_e32 v163, v226
	v_rcp_f32_e32 v224, v224
	v_rcp_f32_e32 v225, v234
	v_rcp_f32_e32 v234, v236
	v_rcp_f32_e32 v235, v235
	v_rcp_f32_e32 v236, v237
	v_rcp_f32_e32 v237, v238
	v_pk_add_f32 v[152:153], v[152:153], v[76:77]
	v_pk_add_f32 v[154:155], v[154:155], v[78:79]
	v_mul_f32_e32 v152, 0xbfb8aa3b, v152
	v_mul_f32_e32 v153, 0xbfb8aa3b, v153
	v_pk_mul_f32 v[162:163], v[162:163], v[164:165]
	v_pk_mul_f32 v[164:165], v[224:225], v[166:167]
	v_exp_f32_e32 v152, v152
	v_exp_f32_e32 v153, v153
	v_mul_f32_e32 v154, 0xbfb8aa3b, v154
	v_mul_f32_e32 v155, 0xbfb8aa3b, v155
	v_pk_mul_f32 v[160:161], v[234:235], v[160:161]
	v_lshlrev_b32_e32 v166, 16, v227
	v_and_b32_e32 v167, 0xffff0000, v227
	v_pk_mul_f32 v[226:227], v[164:165], v[164:165]
	v_pk_mul_f32 v[164:165], v[74:75], v[164:165]
	v_exp_f32_e32 v154, v154
	v_exp_f32_e32 v155, v155
	v_pk_mul_f32 v[166:167], v[236:237], v[166:167]
	v_pk_mul_f32 v[234:235], v[160:161], v[160:161]
	v_pk_mul_f32 v[238:239], v[68:69], v[160:161]
	v_cvt_pk_bf16_f32 v161, v164, v165
	v_lshlrev_b64 v[164:165], 12, v[204:205]
	v_pk_mul_f32 v[224:225], v[162:163], v[162:163]
	v_pk_mul_f32 v[236:237], v[166:167], v[166:167]
	v_pk_mul_f32 v[162:163], v[72:73], v[162:163]
	v_pk_mul_f32 v[166:167], v[70:71], v[166:167]
	v_lshl_add_u64 v[164:165], s[26:27], 0, v[164:165]
	v_pk_add_f32 v[148:149], v[148:149], v[64:65]
	v_cvt_pk_bf16_f32 v160, v162, v163
	v_cvt_pk_bf16_f32 v162, v238, v239
	v_cvt_pk_bf16_f32 v163, v166, v167
	v_lshl_add_u64 v[164:165], v[164:165], 0, v[232:233]
	v_add_f32_e32 v152, 1.0, v152
	v_add_f32_e32 v153, 1.0, v153
	v_mul_f32_e32 v148, 0xbfb8aa3b, v148
	global_store_dwordx4 v[164:165], v[160:163], off
	v_pk_add_f32 v[150:151], v[150:151], v[66:67]
	v_rcp_f32_e32 v152, v152
	v_rcp_f32_e32 v153, v153
	v_add_f32_e32 v154, 1.0, v154
	v_add_f32_e32 v155, 1.0, v155
	v_exp_f32_e32 v162, v148
	v_mul_f32_e32 v148, 0xbfb8aa3b, v149
	v_rcp_f32_e32 v154, v154
	v_rcp_f32_e32 v155, v155
	v_exp_f32_e32 v163, v148
	v_mul_f32_e32 v150, 0xbfb8aa3b, v150
	v_mul_f32_e32 v151, 0xbfb8aa3b, v151
	v_exp_f32_e32 v150, v150
	v_exp_f32_e32 v151, v151
	v_lshlrev_b32_e32 v160, 16, v228
	v_and_b32_e32 v161, 0xffff0000, v228
	v_pk_mul_f32 v[152:153], v[152:153], v[160:161]
	v_lshlrev_b32_e32 v160, 16, v229
	v_and_b32_e32 v161, 0xffff0000, v229
	v_pk_mul_f32 v[148:149], v[154:155], v[160:161]
	v_add_f32_e32 v154, 1.0, v162
	v_add_f32_e32 v155, 1.0, v163
	v_rcp_f32_e32 v154, v154
	v_rcp_f32_e32 v155, v155
	v_add_f32_e32 v150, 1.0, v150
	v_add_f32_e32 v151, 1.0, v151
	v_rcp_f32_e32 v150, v150
	v_rcp_f32_e32 v151, v151
	v_lshlrev_b32_e32 v160, 16, v230
	v_and_b32_e32 v161, 0xffff0000, v230
	v_pk_mul_f32 v[154:155], v[154:155], v[160:161]
	v_lshlrev_b32_e32 v160, 16, v231
	v_and_b32_e32 v161, 0xffff0000, v231
	v_pk_mul_f32 v[150:151], v[150:151], v[160:161]
	v_pk_mul_f32 v[160:161], v[152:153], v[152:153]
	v_pk_mul_f32 v[162:163], v[148:149], v[148:149]
	v_add_f32_e32 v160, v160, v161
	v_add_f32_e32 v162, v162, v163
	v_pk_mul_f32 v[166:167], v[154:155], v[154:155]
	v_add_f32_e32 v160, v160, v162
	v_add_f32_e32 v162, v226, v227
	v_add_f32_e32 v163, v224, v225
	v_pk_mul_f32 v[228:229], v[150:151], v[150:151]
	v_add_f32_e32 v161, v166, v167
	v_add_f32_e32 v162, v163, v162
	v_add_f32_e32 v163, v234, v235
	v_add_f32_e32 v223, v228, v229
	v_add_f32_e32 v160, v161, v160
	v_add_f32_e32 v161, v236, v237
	v_add_f32_e32 v162, v163, v162
	v_add_f32_e32 v160, v223, v160
	v_add_f32_e32 v161, v161, v162
	v_add_f32_e32 v166, v161, v160
	ds_bpermute_b32 v167, v222, v166
	v_pk_mul_f32 v[160:161], v[62:63], v[148:149]
	v_pk_mul_f32 v[148:149], v[60:61], v[152:153]
	v_pk_mul_f32 v[162:163], v[58:59], v[150:151]
	v_cvt_pk_bf16_f32 v150, v148, v149
	s_waitcnt lgkmcnt(0)
	v_add_f32_e32 v148, v166, v167
	ds_bpermute_b32 v149, v221, v148
	v_pk_mul_f32 v[152:153], v[56:57], v[154:155]
	v_cvt_pk_bf16_f32 v151, v160, v161
	v_cvt_pk_bf16_f32 v152, v152, v153
	v_cvt_pk_bf16_f32 v153, v162, v163
	global_store_dwordx4 v[164:165], v[150:153], off offset:256
	s_and_saveexec_b64 s[52:53], s[4:5]
	s_cbranch_execz .LBB0_352
	s_waitcnt lgkmcnt(0)
	v_add_f32_e32 v150, v148, v149
	v_lshlrev_b64 v[148:149], 6, v[204:205]
	v_lshl_add_u64 v[148:149], s[24:25], 0, v[148:149]
	v_lshl_add_u64 v[148:149], s[50:51], 2, v[148:149]
	s_lshl_b32 s20, s68, 2
	v_lshl_add_u64 v[148:149], v[148:149], 0, s[20:21]
	global_store_dword v[148:149], v150, off

.LBB0_459:
	ds_read_b128 v[128:131], v171
	ds_read_b128 v[132:135], v171 offset:1024
	ds_read_b128 v[136:139], v171 offset:2048
	ds_read_b128 v[158:161], v171 offset:3072
	ds_read_b128 v[162:165], v177
	ds_read_b128 v[180:183], v177 offset:1024
	ds_read_b128 v[184:187], v177 offset:2048
	ds_read_b128 v[188:191], v177 offset:3072
	s_add_u32 s40, s38, 0xfff80080
	s_addc_u32 s41, s39, -1
	s_cmp_eq_u32 s67, 28
	s_cselect_b32 s43, s25, s41
	s_cselect_b32 s42, s37, s40
	s_cselect_b32 s41, s23, s65
	s_cselect_b32 s40, s63, s64
	v_lshl_add_u64 v[226:227], s[38:39], 0, v[150:151]
	s_add_i32 m0, s47, 0xc000
	ds_read_b128 v[192:195], v178
	ds_read_b128 v[196:199], v178 offset:1024
	ds_read_b128 v[200:203], v178 offset:2048
	ds_read_b128 v[204:207], v178 offset:3072
	ds_read_b128 v[208:211], v178 offset:4096
	ds_read_b128 v[214:217], v178 offset:5120
	ds_read_b128 v[218:221], v178 offset:6144
	ds_read_b128 v[222:225], v178 offset:7168
	global_load_lds_dwordx4 v[226:227], off
	v_lshl_add_u64 v[226:227], s[38:39], 0, v[152:153]
	s_add_i32 m0, s47, 0xe000
	s_nop 0
	global_load_lds_dwordx4 v[226:227], off
	s_waitcnt vmcnt(8)
	s_waitcnt lgkmcnt(0)
	v_mfma_f32_16x16x32_bf16 v[124:127], v[128:131], v[192:195], v[124:127]
	v_mfma_f32_16x16x32_bf16 v[120:123], v[136:139], v[192:195], v[120:123]
	s_barrier
	s_setprio 1
	s_waitcnt lgkmcnt(0)
	v_mfma_f32_16x16x32_bf16 v[108:111], v[128:131], v[200:203], v[108:111]
	v_mfma_f32_16x16x32_bf16 v[104:107], v[136:139], v[200:203], v[104:107]
	v_mfma_f32_16x16x32_bf16 v[92:95], v[128:131], v[208:211], v[92:95]
	v_mfma_f32_16x16x32_bf16 v[88:91], v[136:139], v[208:211], v[88:91]
	v_mfma_f32_16x16x32_bf16 v[76:79], v[128:131], v[218:221], v[76:79]
	v_mfma_f32_16x16x32_bf16 v[72:75], v[136:139], v[218:221], v[72:75]
	v_mfma_f32_16x16x32_bf16 v[124:127], v[132:135], v[196:199], v[124:127]
	v_mfma_f32_16x16x32_bf16 v[120:123], v[158:161], v[196:199], v[120:123]
	v_mfma_f32_16x16x32_bf16 v[108:111], v[132:135], v[204:207], v[108:111]
	v_mfma_f32_16x16x32_bf16 v[104:107], v[158:161], v[204:207], v[104:107]
	v_mfma_f32_16x16x32_bf16 v[92:95], v[132:135], v[214:217], v[92:95]
	v_mfma_f32_16x16x32_bf16 v[88:91], v[158:161], v[214:217], v[88:91]
	v_mfma_f32_16x16x32_bf16 v[76:79], v[132:135], v[222:225], v[76:79]
	v_mfma_f32_16x16x32_bf16 v[72:75], v[158:161], v[222:225], v[72:75]
	s_setprio 0
	s_setprio 1
	v_mfma_f32_16x16x32_bf16 v[116:119], v[162:165], v[192:195], v[116:119]
	v_mfma_f32_16x16x32_bf16 v[112:115], v[184:187], v[192:195], v[112:115]
	v_mfma_f32_16x16x32_bf16 v[100:103], v[162:165], v[200:203], v[100:103]
	v_mfma_f32_16x16x32_bf16 v[96:99], v[184:187], v[200:203], v[96:99]
	v_mfma_f32_16x16x32_bf16 v[84:87], v[162:165], v[208:211], v[84:87]
	v_mfma_f32_16x16x32_bf16 v[80:83], v[184:187], v[208:211], v[80:83]
	v_mfma_f32_16x16x32_bf16 v[68:71], v[162:165], v[218:221], v[68:71]
	v_mfma_f32_16x16x32_bf16 v[64:67], v[184:187], v[218:221], v[64:67]
	v_mfma_f32_16x16x32_bf16 v[116:119], v[180:183], v[196:199], v[116:119]
	v_mfma_f32_16x16x32_bf16 v[112:115], v[188:191], v[196:199], v[112:115]
	v_mfma_f32_16x16x32_bf16 v[100:103], v[180:183], v[204:207], v[100:103]
	v_mfma_f32_16x16x32_bf16 v[96:99], v[188:191], v[204:207], v[96:99]
	v_mfma_f32_16x16x32_bf16 v[84:87], v[180:183], v[214:217], v[84:87]
	v_mfma_f32_16x16x32_bf16 v[80:83], v[188:191], v[214:217], v[80:83]
	v_mfma_f32_16x16x32_bf16 v[68:71], v[180:183], v[222:225], v[68:71]
	v_mfma_f32_16x16x32_bf16 v[64:67], v[188:191], v[222:225], v[64:67]
	s_setprio 0
	s_barrier
	s_add_i32 s68, s56, s46
	v_lshl_add_u64 v[226:227], s[40:41], 0, v[142:143]
	s_mov_b32 m0, s68
	ds_read_b128 v[192:195], v178 offset:16384
	ds_read_b128 v[196:199], v178 offset:17408
	ds_read_b128 v[200:203], v178 offset:18432
	ds_read_b128 v[204:207], v178 offset:19456
	ds_read_b128 v[208:211], v178 offset:20480
	ds_read_b128 v[214:217], v178 offset:21504
	ds_read_b128 v[218:221], v178 offset:22528
	ds_read_b128 v[222:225], v178 offset:23552
	global_load_lds_dwordx4 v[226:227], off
	s_add_i32 m0, s68, 0x2000
	s_add_u32 s68, s40, 0x80000
	v_lshl_add_u64 v[228:229], s[40:41], 0, v[146:147]
	s_addc_u32 s69, s41, 0
	s_add_i32 s70, s57, s46
	global_load_lds_dwordx4 v[228:229], off
	v_lshl_add_u64 v[230:231], s[68:69], 0, v[142:143]
	s_mov_b32 m0, s70
	v_lshl_add_u64 v[232:233], s[42:43], 0, v[144:145]
	global_load_lds_dwordx4 v[230:231], off
	v_lshl_add_u64 v[230:231], s[68:69], 0, v[146:147]
	s_add_i32 m0, s70, 0x2000
	s_nop 0
	global_load_lds_dwordx4 v[230:231], off
	v_lshl_add_u64 v[230:231], s[42:43], 0, v[140:141]
	s_mov_b32 m0, s47
	s_nop 0
	global_load_lds_dwordx4 v[230:231], off
	s_mov_b32 m0, s48
	s_nop 0
	global_load_lds_dwordx4 v[232:233], off
	s_waitcnt vmcnt(8)
	s_waitcnt lgkmcnt(0)
	v_mfma_f32_16x16x32_bf16 v[60:63], v[128:131], v[192:195], v[60:63]
	v_mfma_f32_16x16x32_bf16 v[56:59], v[136:139], v[192:195], v[56:59]
	s_barrier
	s_setprio 1
	s_waitcnt lgkmcnt(0)
	v_mfma_f32_16x16x32_bf16 v[44:47], v[128:131], v[200:203], v[44:47]
	v_mfma_f32_16x16x32_bf16 v[40:43], v[136:139], v[200:203], v[40:43]
	v_mfma_f32_16x16x32_bf16 v[28:31], v[128:131], v[208:211], v[28:31]
	v_mfma_f32_16x16x32_bf16 v[24:27], v[136:139], v[208:211], v[24:27]
	v_mfma_f32_16x16x32_bf16 v[12:15], v[128:131], v[218:221], v[12:15]
	v_mfma_f32_16x16x32_bf16 v[8:11], v[136:139], v[218:221], v[8:11]
	v_mfma_f32_16x16x32_bf16 v[60:63], v[132:135], v[196:199], v[60:63]
	v_mfma_f32_16x16x32_bf16 v[56:59], v[158:161], v[196:199], v[56:59]
	v_mfma_f32_16x16x32_bf16 v[44:47], v[132:135], v[204:207], v[44:47]
	v_mfma_f32_16x16x32_bf16 v[40:43], v[158:161], v[204:207], v[40:43]
	v_mfma_f32_16x16x32_bf16 v[28:31], v[132:135], v[214:217], v[28:31]
	v_mfma_f32_16x16x32_bf16 v[24:27], v[158:161], v[214:217], v[24:27]
	v_mfma_f32_16x16x32_bf16 v[12:15], v[132:135], v[222:225], v[12:15]
	v_mfma_f32_16x16x32_bf16 v[8:11], v[158:161], v[222:225], v[8:11]
	s_setprio 0
	s_setprio 1
	v_mfma_f32_16x16x32_bf16 v[52:55], v[162:165], v[192:195], v[52:55]
	v_mfma_f32_16x16x32_bf16 v[48:51], v[184:187], v[192:195], v[48:51]
	v_mfma_f32_16x16x32_bf16 v[36:39], v[162:165], v[200:203], v[36:39]
	v_mfma_f32_16x16x32_bf16 v[32:35], v[184:187], v[200:203], v[32:35]
	v_mfma_f32_16x16x32_bf16 v[20:23], v[162:165], v[208:211], v[20:23]
	v_mfma_f32_16x16x32_bf16 v[16:19], v[184:187], v[208:211], v[16:19]
	v_mfma_f32_16x16x32_bf16 v[4:7], v[162:165], v[218:221], v[4:7]
	v_mfma_f32_16x16x32_bf16 v[0:3], v[184:187], v[218:221], v[0:3]
	v_mfma_f32_16x16x32_bf16 v[52:55], v[180:183], v[196:199], v[52:55]
	v_mfma_f32_16x16x32_bf16 v[48:51], v[188:191], v[196:199], v[48:51]
	v_mfma_f32_16x16x32_bf16 v[36:39], v[180:183], v[204:207], v[36:39]
	v_mfma_f32_16x16x32_bf16 v[32:35], v[188:191], v[204:207], v[32:35]
	v_mfma_f32_16x16x32_bf16 v[20:23], v[180:183], v[214:217], v[20:23]
	v_mfma_f32_16x16x32_bf16 v[16:19], v[188:191], v[214:217], v[16:19]
	v_mfma_f32_16x16x32_bf16 v[4:7], v[180:183], v[222:225], v[4:7]
	v_mfma_f32_16x16x32_bf16 v[0:3], v[188:191], v[222:225], v[0:3]
	s_setprio 0
	s_barrier
	s_add_i32 s68, 0, 0x18000
	s_add_i32 s69, 0, 0x1c000
	v_add_u32_e32 v158, s68, v167
	v_add_u32_e32 v188, s69, v167
	ds_read_b128 v[128:131], v158
	ds_read_b128 v[132:135], v158 offset:1024
	ds_read_b128 v[136:139], v158 offset:2048
	ds_read_b128 v[158:161], v158 offset:3072
	ds_read_b128 v[162:165], v188
	ds_read_b128 v[180:183], v188 offset:1024
	ds_read_b128 v[184:187], v188 offset:2048
	ds_read_b128 v[188:191], v188 offset:3072
	s_add_u32 s42, s42, 0x80000
	s_addc_u32 s43, s43, 0
	s_mov_b32 m0, s49
	v_lshl_add_u64 v[234:235], s[42:43], 0, v[140:141]
	ds_read_b128 v[192:195], v178 offset:32768
	ds_read_b128 v[196:199], v178 offset:33792
	ds_read_b128 v[200:203], v178 offset:34816
	ds_read_b128 v[204:207], v178 offset:35840
	ds_read_b128 v[208:211], v178 offset:36864
	ds_read_b128 v[214:217], v178 offset:37888
	ds_read_b128 v[218:221], v178 offset:38912
	ds_read_b128 v[222:225], v178 offset:39936
	global_load_lds_dwordx4 v[234:235], off
	v_lshl_add_u64 v[234:235], s[42:43], 0, v[144:145]
	s_mov_b32 m0, s50
	s_nop 0
	global_load_lds_dwordx4 v[234:235], off
	s_waitcnt vmcnt(8)
	s_waitcnt lgkmcnt(0)
	v_mfma_f32_16x16x32_bf16 v[124:127], v[128:131], v[192:195], v[124:127]
	v_mfma_f32_16x16x32_bf16 v[120:123], v[136:139], v[192:195], v[120:123]
	s_barrier
	s_setprio 1
	s_waitcnt lgkmcnt(0)
	v_mfma_f32_16x16x32_bf16 v[108:111], v[128:131], v[200:203], v[108:111]
	v_mfma_f32_16x16x32_bf16 v[104:107], v[136:139], v[200:203], v[104:107]
	v_mfma_f32_16x16x32_bf16 v[92:95], v[128:131], v[208:211], v[92:95]
	v_mfma_f32_16x16x32_bf16 v[88:91], v[136:139], v[208:211], v[88:91]
	v_mfma_f32_16x16x32_bf16 v[76:79], v[128:131], v[218:221], v[76:79]
	v_mfma_f32_16x16x32_bf16 v[72:75], v[136:139], v[218:221], v[72:75]
	v_mfma_f32_16x16x32_bf16 v[124:127], v[132:135], v[196:199], v[124:127]
	v_mfma_f32_16x16x32_bf16 v[120:123], v[158:161], v[196:199], v[120:123]
	v_mfma_f32_16x16x32_bf16 v[108:111], v[132:135], v[204:207], v[108:111]
	v_mfma_f32_16x16x32_bf16 v[104:107], v[158:161], v[204:207], v[104:107]
	v_mfma_f32_16x16x32_bf16 v[92:95], v[132:135], v[214:217], v[92:95]
	v_mfma_f32_16x16x32_bf16 v[88:91], v[158:161], v[214:217], v[88:91]
	v_mfma_f32_16x16x32_bf16 v[76:79], v[132:135], v[222:225], v[76:79]
	v_mfma_f32_16x16x32_bf16 v[72:75], v[158:161], v[222:225], v[72:75]
	s_setprio 0
	s_setprio 1
	v_mfma_f32_16x16x32_bf16 v[116:119], v[162:165], v[192:195], v[116:119]
	v_mfma_f32_16x16x32_bf16 v[112:115], v[184:187], v[192:195], v[112:115]
	v_mfma_f32_16x16x32_bf16 v[100:103], v[162:165], v[200:203], v[100:103]
	v_mfma_f32_16x16x32_bf16 v[96:99], v[184:187], v[200:203], v[96:99]
	v_mfma_f32_16x16x32_bf16 v[84:87], v[162:165], v[208:211], v[84:87]
	v_mfma_f32_16x16x32_bf16 v[80:83], v[184:187], v[208:211], v[80:83]
	v_mfma_f32_16x16x32_bf16 v[68:71], v[162:165], v[218:221], v[68:71]
	v_mfma_f32_16x16x32_bf16 v[64:67], v[184:187], v[218:221], v[64:67]
	v_mfma_f32_16x16x32_bf16 v[116:119], v[180:183], v[196:199], v[116:119]
	v_mfma_f32_16x16x32_bf16 v[112:115], v[188:191], v[196:199], v[112:115]
	v_mfma_f32_16x16x32_bf16 v[100:103], v[180:183], v[204:207], v[100:103]
	v_mfma_f32_16x16x32_bf16 v[96:99], v[188:191], v[204:207], v[96:99]
	v_mfma_f32_16x16x32_bf16 v[84:87], v[180:183], v[214:217], v[84:87]
	v_mfma_f32_16x16x32_bf16 v[80:83], v[188:191], v[214:217], v[80:83]
	v_mfma_f32_16x16x32_bf16 v[68:71], v[180:183], v[222:225], v[68:71]
	v_mfma_f32_16x16x32_bf16 v[64:67], v[188:191], v[222:225], v[64:67]
	s_setprio 0
	s_barrier
	s_add_i32 s42, s68, s46
	v_lshl_add_u64 v[226:227], v[226:227], 0, s[18:19]
	s_mov_b32 m0, s42
	ds_read_b128 v[192:195], v178 offset:49152
	ds_read_b128 v[196:199], v178 offset:50176
	ds_read_b128 v[200:203], v178 offset:51200
	ds_read_b128 v[204:207], v178 offset:52224
	ds_read_b128 v[208:211], v178 offset:53248
	ds_read_b128 v[214:217], v178 offset:54272
	ds_read_b128 v[218:221], v178 offset:55296
	ds_read_b128 v[222:225], v178 offset:56320
	global_load_lds_dwordx4 v[226:227], off
	s_add_i32 m0, s42, 0x2000
	s_add_u32 s40, s40, 0x80080
	v_lshl_add_u64 v[226:227], v[228:229], 0, s[18:19]
	s_addc_u32 s41, s41, 0
	s_add_i32 s42, s69, s46
	global_load_lds_dwordx4 v[226:227], off
	v_lshl_add_u64 v[226:227], s[40:41], 0, v[142:143]
	s_mov_b32 m0, s42
	s_nop 0
	global_load_lds_dwordx4 v[226:227], off
	v_lshl_add_u64 v[226:227], s[40:41], 0, v[146:147]
	s_add_i32 m0, s42, 0x2000
	s_nop 0
	global_load_lds_dwordx4 v[226:227], off
	v_lshl_add_u64 v[226:227], v[230:231], 0, s[18:19]
	s_mov_b32 m0, s52
	s_nop 0
	global_load_lds_dwordx4 v[226:227], off
	v_lshl_add_u64 v[226:227], v[232:233], 0, s[18:19]
	s_mov_b32 m0, s53
	s_nop 0
	global_load_lds_dwordx4 v[226:227], off
	s_waitcnt vmcnt(8)
	s_waitcnt lgkmcnt(0)
	v_mfma_f32_16x16x32_bf16 v[60:63], v[128:131], v[192:195], v[60:63]
	v_mfma_f32_16x16x32_bf16 v[56:59], v[136:139], v[192:195], v[56:59]
	s_barrier
	s_setprio 1
	s_waitcnt lgkmcnt(0)
	v_mfma_f32_16x16x32_bf16 v[44:47], v[128:131], v[200:203], v[44:47]
	v_mfma_f32_16x16x32_bf16 v[40:43], v[136:139], v[200:203], v[40:43]
	v_mfma_f32_16x16x32_bf16 v[28:31], v[128:131], v[208:211], v[28:31]
	v_mfma_f32_16x16x32_bf16 v[24:27], v[136:139], v[208:211], v[24:27]
	v_mfma_f32_16x16x32_bf16 v[12:15], v[128:131], v[218:221], v[12:15]
	v_mfma_f32_16x16x32_bf16 v[8:11], v[136:139], v[218:221], v[8:11]
	v_mfma_f32_16x16x32_bf16 v[60:63], v[132:135], v[196:199], v[60:63]
	v_mfma_f32_16x16x32_bf16 v[56:59], v[158:161], v[196:199], v[56:59]
	v_mfma_f32_16x16x32_bf16 v[44:47], v[132:135], v[204:207], v[44:47]
	v_mfma_f32_16x16x32_bf16 v[40:43], v[158:161], v[204:207], v[40:43]
	v_mfma_f32_16x16x32_bf16 v[28:31], v[132:135], v[214:217], v[28:31]
	v_mfma_f32_16x16x32_bf16 v[24:27], v[158:161], v[214:217], v[24:27]
	v_mfma_f32_16x16x32_bf16 v[12:15], v[132:135], v[222:225], v[12:15]
	v_mfma_f32_16x16x32_bf16 v[8:11], v[158:161], v[222:225], v[8:11]
	s_setprio 0
	s_setprio 1
	v_mfma_f32_16x16x32_bf16 v[52:55], v[162:165], v[192:195], v[52:55]
	v_mfma_f32_16x16x32_bf16 v[48:51], v[184:187], v[192:195], v[48:51]
	v_mfma_f32_16x16x32_bf16 v[36:39], v[162:165], v[200:203], v[36:39]
	v_mfma_f32_16x16x32_bf16 v[32:35], v[184:187], v[200:203], v[32:35]
	v_mfma_f32_16x16x32_bf16 v[20:23], v[162:165], v[208:211], v[20:23]
	v_mfma_f32_16x16x32_bf16 v[16:19], v[184:187], v[208:211], v[16:19]
	v_mfma_f32_16x16x32_bf16 v[4:7], v[162:165], v[218:221], v[4:7]
	v_mfma_f32_16x16x32_bf16 v[0:3], v[184:187], v[218:221], v[0:3]
	v_mfma_f32_16x16x32_bf16 v[52:55], v[180:183], v[196:199], v[52:55]
	v_mfma_f32_16x16x32_bf16 v[48:51], v[188:191], v[196:199], v[48:51]
	v_mfma_f32_16x16x32_bf16 v[36:39], v[180:183], v[204:207], v[36:39]
	v_mfma_f32_16x16x32_bf16 v[32:35], v[188:191], v[204:207], v[32:35]
	v_mfma_f32_16x16x32_bf16 v[20:23], v[180:183], v[214:217], v[20:23]
	v_mfma_f32_16x16x32_bf16 v[16:19], v[188:191], v[214:217], v[16:19]
	v_mfma_f32_16x16x32_bf16 v[4:7], v[180:183], v[222:225], v[4:7]
	v_mfma_f32_16x16x32_bf16 v[0:3], v[188:191], v[222:225], v[0:3]
	s_setprio 0
	s_barrier
	s_add_i32 s67, s67, 2
	s_add_u32 s38, s38, 0x100
	s_addc_u32 s39, s39, 0
	s_add_u32 s64, s64, 0x100
	s_addc_u32 s65, s65, 0
	s_cmp_gt_u32 s67, 29
	s_cbranch_scc0 .LBB0_459
	v_lshl_add_u32 v158, s36, 8, v166
	v_ashrrev_i32_e32 v159, 31, v158
	v_lshlrev_b64 v[130:131], 6, v[158:159]
	v_lshl_add_u64 v[130:131], v[148:149], 0, v[130:131]
	global_load_dwordx4 v[180:183], v[130:131], off
	v_lshl_or_b32 v128, s12, 8, v168
	v_ashrrev_i32_e32 v129, 31, v128
	v_lshlrev_b64 v[130:131], 12, v[158:159]
	v_lshl_add_u64 v[130:131], s[14:15], 0, v[130:131]
	v_lshlrev_b64 v[160:161], 1, v[128:129]
	v_lshl_add_u64 v[192:193], v[130:131], 0, v[160:161]
	global_load_dwordx4 v[184:187], v[192:193], off
	global_load_dwordx4 v[188:191], v[192:193], off offset:256
	v_or_b32_e32 v162, 16, v158
	v_ashrrev_i32_e32 v163, 31, v162
	v_lshlrev_b64 v[130:131], 12, v[162:163]
	v_lshlrev_b64 v[128:129], 6, v[162:163]
	v_lshl_add_u64 v[130:131], s[14:15], 0, v[130:131]
	v_lshl_add_u64 v[128:129], v[148:149], 0, v[128:129]
	v_lshl_add_u64 v[164:165], v[130:131], 0, v[160:161]
	global_load_dwordx4 v[136:139], v[128:129], off
	global_load_dwordx4 v[132:135], v[164:165], off
	s_nop 0
	global_load_dwordx4 v[128:131], v[164:165], off offset:256
	s_lshl_b32 s36, s12, 2
	s_ashr_i32 s37, s36, 31
	s_waitcnt vmcnt(0)
	v_mov_b32_e32 v194, v181
	v_mov_b32_e32 v195, v182
	v_mov_b32_e32 v181, v183
	v_pk_add_f32 v[180:181], v[194:195], v[180:181]
	v_lshlrev_b32_e32 v182, 16, v184
	v_add_f32_e32 v194, v180, v181
	ds_bpermute_b32 v195, v169, v194
	v_and_b32_e32 v183, 0xffff0000, v184
	v_lshlrev_b32_e32 v184, 16, v185
	v_and_b32_e32 v185, 0xffff0000, v185
	v_lshlrev_b32_e32 v196, 16, v186
	s_waitcnt lgkmcnt(0)
	v_add_f32_e32 v195, v194, v195
	ds_bpermute_b32 v198, v170, v195
	v_and_b32_e32 v197, 0xffff0000, v186
	v_lshlrev_b32_e32 v180, 16, v187
	v_and_b32_e32 v181, 0xffff0000, v187
	v_lshlrev_b32_e32 v186, 16, v188
	s_waitcnt lgkmcnt(0)
	v_add_f32_e32 v195, v195, v198
	v_fmamk_f32 v195, v195, 0x3a800000, v179
	v_mul_f32_e32 v198, 0x4b800000, v195
	v_cmp_gt_f32_e32 vcc, s58, v195
	v_and_b32_e32 v187, 0xffff0000, v188
	v_lshlrev_b32_e32 v188, 16, v189
	v_cndmask_b32_e32 v195, v195, v198, vcc
	v_rsq_f32_e32 v198, v195
	v_and_b32_e32 v189, 0xffff0000, v189
	v_lshlrev_b32_e32 v194, 16, v190
	v_and_b32_e32 v195, 0xffff0000, v190
	v_mul_f32_e32 v199, 0x45800000, v198
	v_lshlrev_b32_e32 v190, 16, v191
	v_and_b32_e32 v191, 0xffff0000, v191
	v_cndmask_b32_e32 v198, v198, v199, vcc
	v_pk_fma_f32 v[126:127], v[126:127], v[198:199], v[184:185] op_sel_hi:[1,0,1]
	v_pk_fma_f32 v[124:125], v[124:125], v[198:199], v[182:183] op_sel_hi:[1,0,1]
	v_pk_fma_f32 v[122:123], v[122:123], v[198:199], v[180:181] op_sel_hi:[1,0,1]
	v_pk_fma_f32 v[120:121], v[120:121], v[198:199], v[196:197] op_sel_hi:[1,0,1]
	v_pk_fma_f32 v[118:119], v[118:119], v[198:199], v[188:189] op_sel_hi:[1,0,1]
	v_pk_fma_f32 v[116:117], v[116:117], v[198:199], v[186:187] op_sel_hi:[1,0,1]
	v_pk_fma_f32 v[180:181], v[114:115], v[198:199], v[190:191] op_sel_hi:[1,0,1]
	v_pk_fma_f32 v[182:183], v[112:113], v[198:199], v[194:195] op_sel_hi:[1,0,1]
	v_cvt_pk_bf16_f32 v112, v124, v125
	v_cvt_pk_bf16_f32 v113, v126, v127
	v_mul_f32_e32 v114, v125, v125
	v_mul_f32_e32 v115, v127, v127
	v_mul_f32_e32 v125, v121, v121
	v_mul_f32_e32 v127, v123, v123
	v_mul_f32_e32 v184, v117, v117
	v_mul_f32_e32 v185, v119, v119
	v_mul_f32_e32 v186, v183, v183
	v_mul_f32_e32 v187, v181, v181
	v_fmac_f32_e32 v114, v124, v124
	v_fmac_f32_e32 v115, v126, v126
	v_fmac_f32_e32 v125, v120, v120
	v_fmac_f32_e32 v127, v122, v122
	v_fmac_f32_e32 v184, v116, v116
	v_fmac_f32_e32 v185, v118, v118
	v_fmac_f32_e32 v186, v182, v182
	v_fmac_f32_e32 v187, v180, v180
	v_add_f32_e32 v114, v114, v115
	v_add_f32_e32 v115, v125, v127
	v_add_f32_e32 v124, v184, v185
	v_add_f32_e32 v125, v186, v187
	v_add_f32_e32 v114, v114, v115
	v_add_f32_e32 v115, v124, v125
	v_add_f32_e32 v124, v114, v115
	ds_bpermute_b32 v125, v169, v124
	v_cvt_pk_bf16_f32 v114, v120, v121
	v_cvt_pk_bf16_f32 v115, v122, v123
	global_store_dwordx4 v[192:193], v[112:115], off
	s_waitcnt lgkmcnt(0)
	s_nop 0
	v_add_f32_e32 v112, v124, v125
	ds_bpermute_b32 v113, v170, v112
	v_cvt_pk_bf16_f32 v114, v116, v117
	v_cvt_pk_bf16_f32 v115, v118, v119
	v_cvt_pk_bf16_f32 v116, v182, v183
	v_cvt_pk_bf16_f32 v117, v180, v181
	global_store_dwordx4 v[192:193], v[114:117], off offset:256
	s_and_saveexec_b64 s[38:39], s[6:7]
	s_cbranch_execz .LBB0_462
	s_waitcnt lgkmcnt(0)
	v_add_f32_e32 v114, v112, v113
	v_lshlrev_b64 v[112:113], 7, v[158:159]
	v_lshl_add_u64 v[112:113], s[0:1], 0, v[112:113]
	v_lshl_add_u64 v[112:113], s[36:37], 2, v[112:113]
	s_lshl_b32 s12, s51, 2
	v_lshl_add_u64 v[112:113], v[112:113], 0, s[12:13]
	global_store_dword v[112:113], v114, off

.LBB0_506:
	ds_read_b128 v[146:149], v183
	ds_read_b128 v[150:153], v183 offset:1024
	ds_read_b128 v[154:157], v183 offset:2048
	ds_read_b128 v[158:161], v183 offset:3072
	ds_read_b128 v[162:165], v184
	ds_read_b128 v[166:169], v184 offset:1024
	ds_read_b128 v[186:189], v184 offset:2048
	ds_read_b128 v[190:193], v184 offset:3072
	s_add_u32 s12, s0, 0xfff80080
	s_addc_u32 s13, s1, -1
	s_cmp_eq_u32 s70, 28
	s_cselect_b32 s47, s9, s13
	s_cselect_b32 s46, s41, s12
	s_cselect_b32 s13, s39, s69
	s_cselect_b32 s12, s67, s68
	v_lshl_add_u64 v[170:171], s[0:1], 0, v[138:139]
	s_add_i32 m0, s50, 0xc000
	ds_read_b128 v[194:197], v185
	ds_read_b128 v[198:201], v185 offset:1024
	ds_read_b128 v[202:205], v185 offset:2048
	ds_read_b128 v[206:209], v185 offset:3072
	ds_read_b128 v[214:217], v185 offset:4096
	ds_read_b128 v[218:221], v185 offset:5120
	ds_read_b128 v[222:225], v185 offset:6144
	ds_read_b128 v[226:229], v185 offset:7168
	global_load_lds_dwordx4 v[170:171], off
	v_lshl_add_u64 v[170:171], s[0:1], 0, v[140:141]
	s_add_i32 m0, s50, 0xe000
	s_nop 0
	global_load_lds_dwordx4 v[170:171], off
	s_waitcnt vmcnt(8)
	s_waitcnt lgkmcnt(0)
	v_mfma_f32_16x16x32_bf16 v[124:127], v[146:149], v[194:197], v[124:127]
	v_mfma_f32_16x16x32_bf16 v[120:123], v[154:157], v[194:197], v[120:123]
	s_barrier
	s_setprio 1
	s_waitcnt lgkmcnt(0)
	v_mfma_f32_16x16x32_bf16 v[108:111], v[146:149], v[202:205], v[108:111]
	v_mfma_f32_16x16x32_bf16 v[104:107], v[154:157], v[202:205], v[104:107]
	v_mfma_f32_16x16x32_bf16 v[92:95], v[146:149], v[214:217], v[92:95]
	v_mfma_f32_16x16x32_bf16 v[88:91], v[154:157], v[214:217], v[88:91]
	v_mfma_f32_16x16x32_bf16 v[76:79], v[146:149], v[222:225], v[76:79]
	v_mfma_f32_16x16x32_bf16 v[72:75], v[154:157], v[222:225], v[72:75]
	v_mfma_f32_16x16x32_bf16 v[124:127], v[150:153], v[198:201], v[124:127]
	v_mfma_f32_16x16x32_bf16 v[120:123], v[158:161], v[198:201], v[120:123]
	v_mfma_f32_16x16x32_bf16 v[108:111], v[150:153], v[206:209], v[108:111]
	v_mfma_f32_16x16x32_bf16 v[104:107], v[158:161], v[206:209], v[104:107]
	v_mfma_f32_16x16x32_bf16 v[92:95], v[150:153], v[218:221], v[92:95]
	v_mfma_f32_16x16x32_bf16 v[88:91], v[158:161], v[218:221], v[88:91]
	v_mfma_f32_16x16x32_bf16 v[76:79], v[150:153], v[226:229], v[76:79]
	v_mfma_f32_16x16x32_bf16 v[72:75], v[158:161], v[226:229], v[72:75]
	s_setprio 0
	s_setprio 1
	v_mfma_f32_16x16x32_bf16 v[116:119], v[162:165], v[194:197], v[116:119]
	v_mfma_f32_16x16x32_bf16 v[112:115], v[186:189], v[194:197], v[112:115]
	v_mfma_f32_16x16x32_bf16 v[100:103], v[162:165], v[202:205], v[100:103]
	v_mfma_f32_16x16x32_bf16 v[96:99], v[186:189], v[202:205], v[96:99]
	v_mfma_f32_16x16x32_bf16 v[84:87], v[162:165], v[214:217], v[84:87]
	v_mfma_f32_16x16x32_bf16 v[80:83], v[186:189], v[214:217], v[80:83]
	v_mfma_f32_16x16x32_bf16 v[68:71], v[162:165], v[222:225], v[68:71]
	v_mfma_f32_16x16x32_bf16 v[64:67], v[186:189], v[222:225], v[64:67]
	v_mfma_f32_16x16x32_bf16 v[116:119], v[166:169], v[198:201], v[116:119]
	v_mfma_f32_16x16x32_bf16 v[112:115], v[190:193], v[198:201], v[112:115]
	v_mfma_f32_16x16x32_bf16 v[100:103], v[166:169], v[206:209], v[100:103]
	v_mfma_f32_16x16x32_bf16 v[96:99], v[190:193], v[206:209], v[96:99]
	v_mfma_f32_16x16x32_bf16 v[84:87], v[166:169], v[218:221], v[84:87]
	v_mfma_f32_16x16x32_bf16 v[80:83], v[190:193], v[218:221], v[80:83]
	v_mfma_f32_16x16x32_bf16 v[68:71], v[166:169], v[226:229], v[68:71]
	v_mfma_f32_16x16x32_bf16 v[64:67], v[190:193], v[226:229], v[64:67]
	s_setprio 0
	s_barrier
	s_add_i32 s71, s58, s48
	v_lshl_add_u64 v[170:171], s[12:13], 0, v[132:133]
	s_mov_b32 m0, s71
	ds_read_b128 v[194:197], v185 offset:16384
	ds_read_b128 v[198:201], v185 offset:17408
	ds_read_b128 v[202:205], v185 offset:18432
	ds_read_b128 v[206:209], v185 offset:19456
	ds_read_b128 v[214:217], v185 offset:20480
	ds_read_b128 v[218:221], v185 offset:21504
	ds_read_b128 v[222:225], v185 offset:22528
	ds_read_b128 v[226:229], v185 offset:23552
	global_load_lds_dwordx4 v[170:171], off
	s_add_i32 m0, s71, 0x2000
	s_add_u32 s72, s12, 0x80000
	v_lshl_add_u64 v[210:211], s[12:13], 0, v[128:129]
	s_addc_u32 s73, s13, 0
	s_add_i32 s71, s59, s48
	global_load_lds_dwordx4 v[210:211], off
	v_lshl_add_u64 v[230:231], s[72:73], 0, v[132:133]
	s_mov_b32 m0, s71
	v_lshl_add_u64 v[232:233], s[46:47], 0, v[130:131]
	global_load_lds_dwordx4 v[230:231], off
	v_lshl_add_u64 v[230:231], s[72:73], 0, v[128:129]
	s_add_i32 m0, s71, 0x2000
	s_nop 0
	global_load_lds_dwordx4 v[230:231], off
	v_lshl_add_u64 v[230:231], s[46:47], 0, v[134:135]
	s_mov_b32 m0, s50
	s_nop 0
	global_load_lds_dwordx4 v[230:231], off
	s_mov_b32 m0, s51
	s_nop 0
	global_load_lds_dwordx4 v[232:233], off
	s_waitcnt vmcnt(8)
	s_waitcnt lgkmcnt(0)
	v_mfma_f32_16x16x32_bf16 v[60:63], v[146:149], v[194:197], v[60:63]
	v_mfma_f32_16x16x32_bf16 v[56:59], v[154:157], v[194:197], v[56:59]
	s_barrier
	s_setprio 1
	s_waitcnt lgkmcnt(0)
	v_mfma_f32_16x16x32_bf16 v[44:47], v[146:149], v[202:205], v[44:47]
	v_mfma_f32_16x16x32_bf16 v[40:43], v[154:157], v[202:205], v[40:43]
	v_mfma_f32_16x16x32_bf16 v[28:31], v[146:149], v[214:217], v[28:31]
	v_mfma_f32_16x16x32_bf16 v[24:27], v[154:157], v[214:217], v[24:27]
	v_mfma_f32_16x16x32_bf16 v[12:15], v[146:149], v[222:225], v[12:15]
	v_mfma_f32_16x16x32_bf16 v[8:11], v[154:157], v[222:225], v[8:11]
	v_mfma_f32_16x16x32_bf16 v[60:63], v[150:153], v[198:201], v[60:63]
	v_mfma_f32_16x16x32_bf16 v[56:59], v[158:161], v[198:201], v[56:59]
	v_mfma_f32_16x16x32_bf16 v[44:47], v[150:153], v[206:209], v[44:47]
	v_mfma_f32_16x16x32_bf16 v[40:43], v[158:161], v[206:209], v[40:43]
	v_mfma_f32_16x16x32_bf16 v[28:31], v[150:153], v[218:221], v[28:31]
	v_mfma_f32_16x16x32_bf16 v[24:27], v[158:161], v[218:221], v[24:27]
	v_mfma_f32_16x16x32_bf16 v[12:15], v[150:153], v[226:229], v[12:15]
	v_mfma_f32_16x16x32_bf16 v[8:11], v[158:161], v[226:229], v[8:11]
	s_setprio 0
	s_setprio 1
	v_mfma_f32_16x16x32_bf16 v[52:55], v[162:165], v[194:197], v[52:55]
	v_mfma_f32_16x16x32_bf16 v[48:51], v[186:189], v[194:197], v[48:51]
	v_mfma_f32_16x16x32_bf16 v[36:39], v[162:165], v[202:205], v[36:39]
	v_mfma_f32_16x16x32_bf16 v[32:35], v[186:189], v[202:205], v[32:35]
	v_mfma_f32_16x16x32_bf16 v[20:23], v[162:165], v[214:217], v[20:23]
	v_mfma_f32_16x16x32_bf16 v[16:19], v[186:189], v[214:217], v[16:19]
	v_mfma_f32_16x16x32_bf16 v[4:7], v[162:165], v[222:225], v[4:7]
	v_mfma_f32_16x16x32_bf16 v[0:3], v[186:189], v[222:225], v[0:3]
	v_mfma_f32_16x16x32_bf16 v[52:55], v[166:169], v[198:201], v[52:55]
	v_mfma_f32_16x16x32_bf16 v[48:51], v[190:193], v[198:201], v[48:51]
	v_mfma_f32_16x16x32_bf16 v[36:39], v[166:169], v[206:209], v[36:39]
	v_mfma_f32_16x16x32_bf16 v[32:35], v[190:193], v[206:209], v[32:35]
	v_mfma_f32_16x16x32_bf16 v[20:23], v[166:169], v[218:221], v[20:23]
	v_mfma_f32_16x16x32_bf16 v[16:19], v[190:193], v[218:221], v[16:19]
	v_mfma_f32_16x16x32_bf16 v[4:7], v[166:169], v[226:229], v[4:7]
	v_mfma_f32_16x16x32_bf16 v[0:3], v[190:193], v[226:229], v[0:3]
	s_setprio 0
	s_barrier
	s_add_i32 s71, 0, 0x18000
	s_add_i32 s72, 0, 0x1c000
	v_add_u32_e32 v158, s71, v178
	v_add_u32_e32 v190, s72, v178
	ds_read_b128 v[146:149], v158
	ds_read_b128 v[150:153], v158 offset:1024
	ds_read_b128 v[154:157], v158 offset:2048
	ds_read_b128 v[158:161], v158 offset:3072
	ds_read_b128 v[162:165], v190
	ds_read_b128 v[166:169], v190 offset:1024
	ds_read_b128 v[186:189], v190 offset:2048
	ds_read_b128 v[190:193], v190 offset:3072
	s_add_u32 s46, s46, 0x80000
	s_addc_u32 s47, s47, 0
	s_mov_b32 m0, s52
	v_lshl_add_u64 v[234:235], s[46:47], 0, v[134:135]
	ds_read_b128 v[194:197], v185 offset:32768
	ds_read_b128 v[198:201], v185 offset:33792
	ds_read_b128 v[202:205], v185 offset:34816
	ds_read_b128 v[206:209], v185 offset:35840
	ds_read_b128 v[214:217], v185 offset:36864
	ds_read_b128 v[218:221], v185 offset:37888
	ds_read_b128 v[222:225], v185 offset:38912
	ds_read_b128 v[226:229], v185 offset:39936
	global_load_lds_dwordx4 v[234:235], off
	v_lshl_add_u64 v[234:235], s[46:47], 0, v[130:131]
	s_mov_b32 m0, s53
	s_nop 0
	global_load_lds_dwordx4 v[234:235], off
	s_waitcnt vmcnt(8)
	s_waitcnt lgkmcnt(0)
	v_mfma_f32_16x16x32_bf16 v[124:127], v[146:149], v[194:197], v[124:127]
	v_mfma_f32_16x16x32_bf16 v[120:123], v[154:157], v[194:197], v[120:123]
	s_barrier
	s_setprio 1
	s_waitcnt lgkmcnt(0)
	v_mfma_f32_16x16x32_bf16 v[108:111], v[146:149], v[202:205], v[108:111]
	v_mfma_f32_16x16x32_bf16 v[104:107], v[154:157], v[202:205], v[104:107]
	v_mfma_f32_16x16x32_bf16 v[92:95], v[146:149], v[214:217], v[92:95]
	v_mfma_f32_16x16x32_bf16 v[88:91], v[154:157], v[214:217], v[88:91]
	v_mfma_f32_16x16x32_bf16 v[76:79], v[146:149], v[222:225], v[76:79]
	v_mfma_f32_16x16x32_bf16 v[72:75], v[154:157], v[222:225], v[72:75]
	v_mfma_f32_16x16x32_bf16 v[124:127], v[150:153], v[198:201], v[124:127]
	v_mfma_f32_16x16x32_bf16 v[120:123], v[158:161], v[198:201], v[120:123]
	v_mfma_f32_16x16x32_bf16 v[108:111], v[150:153], v[206:209], v[108:111]
	v_mfma_f32_16x16x32_bf16 v[104:107], v[158:161], v[206:209], v[104:107]
	v_mfma_f32_16x16x32_bf16 v[92:95], v[150:153], v[218:221], v[92:95]
	v_mfma_f32_16x16x32_bf16 v[88:91], v[158:161], v[218:221], v[88:91]
	v_mfma_f32_16x16x32_bf16 v[76:79], v[150:153], v[226:229], v[76:79]
	v_mfma_f32_16x16x32_bf16 v[72:75], v[158:161], v[226:229], v[72:75]
	s_setprio 0
	s_setprio 1
	v_mfma_f32_16x16x32_bf16 v[116:119], v[162:165], v[194:197], v[116:119]
	v_mfma_f32_16x16x32_bf16 v[112:115], v[186:189], v[194:197], v[112:115]
	v_mfma_f32_16x16x32_bf16 v[100:103], v[162:165], v[202:205], v[100:103]
	v_mfma_f32_16x16x32_bf16 v[96:99], v[186:189], v[202:205], v[96:99]
	v_mfma_f32_16x16x32_bf16 v[84:87], v[162:165], v[214:217], v[84:87]
	v_mfma_f32_16x16x32_bf16 v[80:83], v[186:189], v[214:217], v[80:83]
	v_mfma_f32_16x16x32_bf16 v[68:71], v[162:165], v[222:225], v[68:71]
	v_mfma_f32_16x16x32_bf16 v[64:67], v[186:189], v[222:225], v[64:67]
	v_mfma_f32_16x16x32_bf16 v[116:119], v[166:169], v[198:201], v[116:119]
	v_mfma_f32_16x16x32_bf16 v[112:115], v[190:193], v[198:201], v[112:115]
	v_mfma_f32_16x16x32_bf16 v[100:103], v[166:169], v[206:209], v[100:103]
	v_mfma_f32_16x16x32_bf16 v[96:99], v[190:193], v[206:209], v[96:99]
	v_mfma_f32_16x16x32_bf16 v[84:87], v[166:169], v[218:221], v[84:87]
	v_mfma_f32_16x16x32_bf16 v[80:83], v[190:193], v[218:221], v[80:83]
	v_mfma_f32_16x16x32_bf16 v[68:71], v[166:169], v[226:229], v[68:71]
	v_mfma_f32_16x16x32_bf16 v[64:67], v[190:193], v[226:229], v[64:67]
	s_setprio 0
	s_barrier
	s_add_i32 s46, s71, s48
	v_lshl_add_u64 v[170:171], v[170:171], 0, s[22:23]
	s_mov_b32 m0, s46
	ds_read_b128 v[194:197], v185 offset:49152
	ds_read_b128 v[198:201], v185 offset:50176
	ds_read_b128 v[202:205], v185 offset:51200
	ds_read_b128 v[206:209], v185 offset:52224
	ds_read_b128 v[214:217], v185 offset:53248
	ds_read_b128 v[218:221], v185 offset:54272
	ds_read_b128 v[222:225], v185 offset:55296
	ds_read_b128 v[226:229], v185 offset:56320
	global_load_lds_dwordx4 v[170:171], off
	s_add_i32 m0, s46, 0x2000
	s_add_u32 s12, s12, 0x80080
	v_lshl_add_u64 v[170:171], v[210:211], 0, s[22:23]
	s_addc_u32 s13, s13, 0
	s_add_i32 s46, s72, s48
	global_load_lds_dwordx4 v[170:171], off
	v_lshl_add_u64 v[170:171], s[12:13], 0, v[132:133]
	s_mov_b32 m0, s46
	s_nop 0
	global_load_lds_dwordx4 v[170:171], off
	v_lshl_add_u64 v[170:171], s[12:13], 0, v[128:129]
	s_add_i32 m0, s46, 0x2000
	s_nop 0
	global_load_lds_dwordx4 v[170:171], off
	v_lshl_add_u64 v[170:171], v[230:231], 0, s[22:23]
	s_mov_b32 m0, s55
	s_nop 0
	global_load_lds_dwordx4 v[170:171], off
	v_lshl_add_u64 v[170:171], v[232:233], 0, s[22:23]
	s_mov_b32 m0, s56
	s_nop 0
	global_load_lds_dwordx4 v[170:171], off
	s_waitcnt vmcnt(8)
	s_waitcnt lgkmcnt(0)
	v_mfma_f32_16x16x32_bf16 v[60:63], v[146:149], v[194:197], v[60:63]
	v_mfma_f32_16x16x32_bf16 v[56:59], v[154:157], v[194:197], v[56:59]
	s_barrier
	s_setprio 1
	s_waitcnt lgkmcnt(0)
	v_mfma_f32_16x16x32_bf16 v[44:47], v[146:149], v[202:205], v[44:47]
	v_mfma_f32_16x16x32_bf16 v[40:43], v[154:157], v[202:205], v[40:43]
	v_mfma_f32_16x16x32_bf16 v[28:31], v[146:149], v[214:217], v[28:31]
	v_mfma_f32_16x16x32_bf16 v[24:27], v[154:157], v[214:217], v[24:27]
	v_mfma_f32_16x16x32_bf16 v[12:15], v[146:149], v[222:225], v[12:15]
	v_mfma_f32_16x16x32_bf16 v[8:11], v[154:157], v[222:225], v[8:11]
	v_mfma_f32_16x16x32_bf16 v[60:63], v[150:153], v[198:201], v[60:63]
	v_mfma_f32_16x16x32_bf16 v[56:59], v[158:161], v[198:201], v[56:59]
	v_mfma_f32_16x16x32_bf16 v[44:47], v[150:153], v[206:209], v[44:47]
	v_mfma_f32_16x16x32_bf16 v[40:43], v[158:161], v[206:209], v[40:43]
	v_mfma_f32_16x16x32_bf16 v[28:31], v[150:153], v[218:221], v[28:31]
	v_mfma_f32_16x16x32_bf16 v[24:27], v[158:161], v[218:221], v[24:27]
	v_mfma_f32_16x16x32_bf16 v[12:15], v[150:153], v[226:229], v[12:15]
	v_mfma_f32_16x16x32_bf16 v[8:11], v[158:161], v[226:229], v[8:11]
	s_setprio 0
	s_setprio 1
	v_mfma_f32_16x16x32_bf16 v[52:55], v[162:165], v[194:197], v[52:55]
	v_mfma_f32_16x16x32_bf16 v[48:51], v[186:189], v[194:197], v[48:51]
	v_mfma_f32_16x16x32_bf16 v[36:39], v[162:165], v[202:205], v[36:39]
	v_mfma_f32_16x16x32_bf16 v[32:35], v[186:189], v[202:205], v[32:35]
	v_mfma_f32_16x16x32_bf16 v[20:23], v[162:165], v[214:217], v[20:23]
	v_mfma_f32_16x16x32_bf16 v[16:19], v[186:189], v[214:217], v[16:19]
	v_mfma_f32_16x16x32_bf16 v[4:7], v[162:165], v[222:225], v[4:7]
	v_mfma_f32_16x16x32_bf16 v[0:3], v[186:189], v[222:225], v[0:3]
	v_mfma_f32_16x16x32_bf16 v[52:55], v[166:169], v[198:201], v[52:55]
	v_mfma_f32_16x16x32_bf16 v[48:51], v[190:193], v[198:201], v[48:51]
	v_mfma_f32_16x16x32_bf16 v[36:39], v[166:169], v[206:209], v[36:39]
	v_mfma_f32_16x16x32_bf16 v[32:35], v[190:193], v[206:209], v[32:35]
	v_mfma_f32_16x16x32_bf16 v[20:23], v[166:169], v[218:221], v[20:23]
	v_mfma_f32_16x16x32_bf16 v[16:19], v[190:193], v[218:221], v[16:19]
	v_mfma_f32_16x16x32_bf16 v[4:7], v[166:169], v[226:229], v[4:7]
	v_mfma_f32_16x16x32_bf16 v[0:3], v[190:193], v[226:229], v[0:3]
	s_setprio 0
	s_barrier
	s_add_i32 s70, s70, 2
	s_add_u32 s0, s0, 0x100
	s_addc_u32 s1, s1, 0
	s_add_u32 s68, s68, 0x100
	s_addc_u32 s69, s69, 0
	s_cmp_gt_u32 s70, 29
	s_cbranch_scc0 .LBB0_506
	s_and_b64 vcc, exec, s[24:25]
	s_cbranch_vccz .LBB0_509
	s_barrier

.LBB0_550:
	ds_read_b128 v[144:147], v155
	ds_read_b128 v[148:151], v155 offset:1024
	ds_read_b128 v[158:161], v155 offset:2048
	ds_read_b128 v[162:165], v155 offset:3072
	ds_read_b128 v[166:169], v156
	ds_read_b128 v[178:181], v156 offset:1024
	ds_read_b128 v[182:185], v156 offset:2048
	ds_read_b128 v[186:189], v156 offset:3072
	s_add_u32 s34, s26, 0x100
	s_addc_u32 s35, s27, 0
	s_cmpk_eq_i32 s63, 0x54
	s_cselect_b32 s39, s1, s35
	s_cselect_b32 s38, s0, s34
	s_cselect_b32 s37, s7, s59
	s_cselect_b32 s36, s6, s58
	v_lshl_add_u64 v[170:171], s[26:27], 0, v[136:137]
	s_add_i32 m0, s44, 0xc000
	ds_read_b128 v[190:193], v157
	ds_read_b128 v[194:197], v157 offset:1024
	ds_read_b128 v[198:201], v157 offset:2048
	ds_read_b128 v[202:205], v157 offset:3072
	ds_read_b128 v[206:209], v157 offset:4096
	ds_read_b128 v[214:217], v157 offset:5120
	ds_read_b128 v[218:221], v157 offset:6144
	ds_read_b128 v[222:225], v157 offset:7168
	global_load_lds_dwordx4 v[170:171], off
	v_lshl_add_u64 v[170:171], s[26:27], 0, v[138:139]
	s_add_i32 m0, s44, 0xe000
	s_nop 0
	global_load_lds_dwordx4 v[170:171], off
	s_waitcnt vmcnt(8)
	s_waitcnt lgkmcnt(0)
	v_mfma_f32_16x16x32_bf16 v[124:127], v[144:147], v[190:193], v[124:127]
	v_mfma_f32_16x16x32_bf16 v[120:123], v[158:161], v[190:193], v[120:123]
	s_barrier
	s_setprio 1
	s_waitcnt lgkmcnt(0)
	v_mfma_f32_16x16x32_bf16 v[116:119], v[144:147], v[198:201], v[116:119]
	v_mfma_f32_16x16x32_bf16 v[112:115], v[158:161], v[198:201], v[112:115]
	v_mfma_f32_16x16x32_bf16 v[92:95], v[144:147], v[206:209], v[92:95]
	v_mfma_f32_16x16x32_bf16 v[88:91], v[158:161], v[206:209], v[88:91]
	v_mfma_f32_16x16x32_bf16 v[84:87], v[144:147], v[218:221], v[84:87]
	v_mfma_f32_16x16x32_bf16 v[80:83], v[158:161], v[218:221], v[80:83]
	v_mfma_f32_16x16x32_bf16 v[124:127], v[148:151], v[194:197], v[124:127]
	v_mfma_f32_16x16x32_bf16 v[120:123], v[162:165], v[194:197], v[120:123]
	v_mfma_f32_16x16x32_bf16 v[116:119], v[148:151], v[202:205], v[116:119]
	v_mfma_f32_16x16x32_bf16 v[112:115], v[162:165], v[202:205], v[112:115]
	v_mfma_f32_16x16x32_bf16 v[92:95], v[148:151], v[214:217], v[92:95]
	v_mfma_f32_16x16x32_bf16 v[88:91], v[162:165], v[214:217], v[88:91]
	v_mfma_f32_16x16x32_bf16 v[84:87], v[148:151], v[222:225], v[84:87]
	v_mfma_f32_16x16x32_bf16 v[80:83], v[162:165], v[222:225], v[80:83]
	s_setprio 0
	s_setprio 1
	v_mfma_f32_16x16x32_bf16 v[108:111], v[166:169], v[190:193], v[108:111]
	v_mfma_f32_16x16x32_bf16 v[104:107], v[182:185], v[190:193], v[104:107]
	v_mfma_f32_16x16x32_bf16 v[100:103], v[166:169], v[198:201], v[100:103]
	v_mfma_f32_16x16x32_bf16 v[96:99], v[182:185], v[198:201], v[96:99]
	v_mfma_f32_16x16x32_bf16 v[76:79], v[166:169], v[206:209], v[76:79]
	v_mfma_f32_16x16x32_bf16 v[72:75], v[182:185], v[206:209], v[72:75]
	v_mfma_f32_16x16x32_bf16 v[68:71], v[166:169], v[218:221], v[68:71]
	v_mfma_f32_16x16x32_bf16 v[64:67], v[182:185], v[218:221], v[64:67]
	v_mfma_f32_16x16x32_bf16 v[108:111], v[178:181], v[194:197], v[108:111]
	v_mfma_f32_16x16x32_bf16 v[104:107], v[186:189], v[194:197], v[104:107]
	v_mfma_f32_16x16x32_bf16 v[100:103], v[178:181], v[202:205], v[100:103]
	v_mfma_f32_16x16x32_bf16 v[96:99], v[186:189], v[202:205], v[96:99]
	v_mfma_f32_16x16x32_bf16 v[76:79], v[178:181], v[214:217], v[76:79]
	v_mfma_f32_16x16x32_bf16 v[72:75], v[186:189], v[214:217], v[72:75]
	v_mfma_f32_16x16x32_bf16 v[68:71], v[178:181], v[222:225], v[68:71]
	v_mfma_f32_16x16x32_bf16 v[64:67], v[186:189], v[222:225], v[64:67]
	s_setprio 0
	s_barrier
	s_add_i32 s26, s52, s43
	v_lshl_add_u64 v[170:171], s[36:37], 0, v[130:131]
	s_mov_b32 m0, s26
	ds_read_b128 v[190:193], v157 offset:16384
	ds_read_b128 v[194:197], v157 offset:17408
	ds_read_b128 v[198:201], v157 offset:18432
	ds_read_b128 v[202:205], v157 offset:19456
	ds_read_b128 v[206:209], v157 offset:20480
	ds_read_b128 v[214:217], v157 offset:21504
	ds_read_b128 v[218:221], v157 offset:22528
	ds_read_b128 v[222:225], v157 offset:23552
	global_load_lds_dwordx4 v[170:171], off
	s_add_i32 m0, s26, 0x2000
	s_add_u32 s26, s36, 0x160000
	v_lshl_add_u64 v[210:211], s[36:37], 0, v[134:135]
	s_addc_u32 s27, s37, 0
	s_add_i32 s64, s53, s43
	global_load_lds_dwordx4 v[210:211], off
	v_lshl_add_u64 v[226:227], s[26:27], 0, v[130:131]
	s_mov_b32 m0, s64
	v_lshl_add_u64 v[228:229], s[38:39], 0, v[132:133]
	global_load_lds_dwordx4 v[226:227], off
	v_lshl_add_u64 v[226:227], s[26:27], 0, v[134:135]
	s_add_i32 m0, s64, 0x2000
	s_nop 0
	global_load_lds_dwordx4 v[226:227], off
	v_lshl_add_u64 v[226:227], s[38:39], 0, v[128:129]
	s_mov_b32 m0, s44
	s_nop 0
	global_load_lds_dwordx4 v[226:227], off
	s_mov_b32 m0, s45
	s_nop 0
	global_load_lds_dwordx4 v[228:229], off
	s_waitcnt vmcnt(8)
	s_waitcnt lgkmcnt(0)
	v_mfma_f32_16x16x32_bf16 v[60:63], v[144:147], v[190:193], v[60:63]
	v_mfma_f32_16x16x32_bf16 v[56:59], v[158:161], v[190:193], v[56:59]
	s_barrier
	s_setprio 1
	s_waitcnt lgkmcnt(0)
	v_mfma_f32_16x16x32_bf16 v[52:55], v[144:147], v[198:201], v[52:55]
	v_mfma_f32_16x16x32_bf16 v[48:51], v[158:161], v[198:201], v[48:51]
	v_mfma_f32_16x16x32_bf16 v[28:31], v[144:147], v[206:209], v[28:31]
	v_mfma_f32_16x16x32_bf16 v[24:27], v[158:161], v[206:209], v[24:27]
	v_mfma_f32_16x16x32_bf16 v[16:19], v[144:147], v[218:221], v[16:19]
	v_mfma_f32_16x16x32_bf16 v[8:11], v[158:161], v[218:221], v[8:11]
	v_mfma_f32_16x16x32_bf16 v[60:63], v[148:151], v[194:197], v[60:63]
	v_mfma_f32_16x16x32_bf16 v[56:59], v[162:165], v[194:197], v[56:59]
	v_mfma_f32_16x16x32_bf16 v[52:55], v[148:151], v[202:205], v[52:55]
	v_mfma_f32_16x16x32_bf16 v[48:51], v[162:165], v[202:205], v[48:51]
	v_mfma_f32_16x16x32_bf16 v[28:31], v[148:151], v[214:217], v[28:31]
	v_mfma_f32_16x16x32_bf16 v[24:27], v[162:165], v[214:217], v[24:27]
	v_mfma_f32_16x16x32_bf16 v[16:19], v[148:151], v[222:225], v[16:19]
	v_mfma_f32_16x16x32_bf16 v[8:11], v[162:165], v[222:225], v[8:11]
	s_setprio 0
	s_setprio 1
	v_mfma_f32_16x16x32_bf16 v[44:47], v[166:169], v[190:193], v[44:47]
	v_mfma_f32_16x16x32_bf16 v[40:43], v[182:185], v[190:193], v[40:43]
	v_mfma_f32_16x16x32_bf16 v[36:39], v[166:169], v[198:201], v[36:39]
	v_mfma_f32_16x16x32_bf16 v[32:35], v[182:185], v[198:201], v[32:35]
	v_mfma_f32_16x16x32_bf16 v[20:23], v[166:169], v[206:209], v[20:23]
	v_mfma_f32_16x16x32_bf16 v[12:15], v[182:185], v[206:209], v[12:15]
	v_mfma_f32_16x16x32_bf16 v[4:7], v[166:169], v[218:221], v[4:7]
	v_mfma_f32_16x16x32_bf16 v[0:3], v[182:185], v[218:221], v[0:3]
	v_mfma_f32_16x16x32_bf16 v[44:47], v[178:181], v[194:197], v[44:47]
	v_mfma_f32_16x16x32_bf16 v[40:43], v[186:189], v[194:197], v[40:43]
	v_mfma_f32_16x16x32_bf16 v[36:39], v[178:181], v[202:205], v[36:39]
	v_mfma_f32_16x16x32_bf16 v[32:35], v[186:189], v[202:205], v[32:35]
	v_mfma_f32_16x16x32_bf16 v[20:23], v[178:181], v[214:217], v[20:23]
	v_mfma_f32_16x16x32_bf16 v[12:15], v[186:189], v[214:217], v[12:15]
	v_mfma_f32_16x16x32_bf16 v[4:7], v[178:181], v[222:225], v[4:7]
	v_mfma_f32_16x16x32_bf16 v[0:3], v[186:189], v[222:225], v[0:3]
	s_setprio 0
	s_barrier
	s_add_i32 s64, 0, 0x18000
	s_add_i32 s65, 0, 0x1c000
	v_add_u32_e32 v162, s64, v153
	v_add_u32_e32 v177, s65, v153
	ds_read_b128 v[144:147], v162
	ds_read_b128 v[148:151], v162 offset:1024
	ds_read_b128 v[158:161], v162 offset:2048
	ds_read_b128 v[162:165], v162 offset:3072
	ds_read_b128 v[166:169], v177
	ds_read_b128 v[178:181], v177 offset:1024
	ds_read_b128 v[182:185], v177 offset:2048
	ds_read_b128 v[186:189], v177 offset:3072
	s_add_u32 s26, s38, 0x160000
	s_addc_u32 s27, s39, 0
	s_mov_b32 m0, s46
	v_lshl_add_u64 v[230:231], s[26:27], 0, v[128:129]
	ds_read_b128 v[190:193], v157 offset:32768
	ds_read_b128 v[194:197], v157 offset:33792
	ds_read_b128 v[198:201], v157 offset:34816
	ds_read_b128 v[202:205], v157 offset:35840
	ds_read_b128 v[206:209], v157 offset:36864
	ds_read_b128 v[214:217], v157 offset:37888
	ds_read_b128 v[218:221], v157 offset:38912
	ds_read_b128 v[222:225], v157 offset:39936
	global_load_lds_dwordx4 v[230:231], off
	v_lshl_add_u64 v[230:231], s[26:27], 0, v[132:133]
	s_mov_b32 m0, s47
	s_nop 0
	global_load_lds_dwordx4 v[230:231], off
	s_waitcnt vmcnt(8)
	s_waitcnt lgkmcnt(0)
	v_mfma_f32_16x16x32_bf16 v[124:127], v[144:147], v[190:193], v[124:127]
	v_mfma_f32_16x16x32_bf16 v[120:123], v[158:161], v[190:193], v[120:123]
	s_barrier
	s_setprio 1
	s_waitcnt lgkmcnt(0)
	v_mfma_f32_16x16x32_bf16 v[116:119], v[144:147], v[198:201], v[116:119]
	v_mfma_f32_16x16x32_bf16 v[112:115], v[158:161], v[198:201], v[112:115]
	v_mfma_f32_16x16x32_bf16 v[92:95], v[144:147], v[206:209], v[92:95]
	v_mfma_f32_16x16x32_bf16 v[88:91], v[158:161], v[206:209], v[88:91]
	v_mfma_f32_16x16x32_bf16 v[84:87], v[144:147], v[218:221], v[84:87]
	v_mfma_f32_16x16x32_bf16 v[80:83], v[158:161], v[218:221], v[80:83]
	v_mfma_f32_16x16x32_bf16 v[124:127], v[148:151], v[194:197], v[124:127]
	v_mfma_f32_16x16x32_bf16 v[120:123], v[162:165], v[194:197], v[120:123]
	v_mfma_f32_16x16x32_bf16 v[116:119], v[148:151], v[202:205], v[116:119]
	v_mfma_f32_16x16x32_bf16 v[112:115], v[162:165], v[202:205], v[112:115]
	v_mfma_f32_16x16x32_bf16 v[92:95], v[148:151], v[214:217], v[92:95]
	v_mfma_f32_16x16x32_bf16 v[88:91], v[162:165], v[214:217], v[88:91]
	v_mfma_f32_16x16x32_bf16 v[84:87], v[148:151], v[222:225], v[84:87]
	v_mfma_f32_16x16x32_bf16 v[80:83], v[162:165], v[222:225], v[80:83]
	s_setprio 0
	s_setprio 1
	v_mfma_f32_16x16x32_bf16 v[108:111], v[166:169], v[190:193], v[108:111]
	v_mfma_f32_16x16x32_bf16 v[104:107], v[182:185], v[190:193], v[104:107]
	v_mfma_f32_16x16x32_bf16 v[100:103], v[166:169], v[198:201], v[100:103]
	v_mfma_f32_16x16x32_bf16 v[96:99], v[182:185], v[198:201], v[96:99]
	v_mfma_f32_16x16x32_bf16 v[76:79], v[166:169], v[206:209], v[76:79]
	v_mfma_f32_16x16x32_bf16 v[72:75], v[182:185], v[206:209], v[72:75]
	v_mfma_f32_16x16x32_bf16 v[68:71], v[166:169], v[218:221], v[68:71]
	v_mfma_f32_16x16x32_bf16 v[64:67], v[182:185], v[218:221], v[64:67]
	v_mfma_f32_16x16x32_bf16 v[108:111], v[178:181], v[194:197], v[108:111]
	v_mfma_f32_16x16x32_bf16 v[104:107], v[186:189], v[194:197], v[104:107]
	v_mfma_f32_16x16x32_bf16 v[100:103], v[178:181], v[202:205], v[100:103]
	v_mfma_f32_16x16x32_bf16 v[96:99], v[186:189], v[202:205], v[96:99]
	v_mfma_f32_16x16x32_bf16 v[76:79], v[178:181], v[214:217], v[76:79]
	v_mfma_f32_16x16x32_bf16 v[72:75], v[186:189], v[214:217], v[72:75]
	v_mfma_f32_16x16x32_bf16 v[68:71], v[178:181], v[222:225], v[68:71]
	v_mfma_f32_16x16x32_bf16 v[64:67], v[186:189], v[222:225], v[64:67]
	s_setprio 0
	s_barrier
	s_add_i32 s26, s64, s43
	v_lshl_add_u64 v[170:171], v[170:171], 0, s[8:9]
	s_mov_b32 m0, s26
	ds_read_b128 v[190:193], v157 offset:49152
	ds_read_b128 v[194:197], v157 offset:50176
	ds_read_b128 v[198:201], v157 offset:51200
	ds_read_b128 v[202:205], v157 offset:52224
	ds_read_b128 v[206:209], v157 offset:53248
	ds_read_b128 v[214:217], v157 offset:54272
	ds_read_b128 v[218:221], v157 offset:55296
	ds_read_b128 v[222:225], v157 offset:56320
	global_load_lds_dwordx4 v[170:171], off
	s_add_i32 m0, s26, 0x2000
	s_add_u32 s26, s36, 0x160080
	v_lshl_add_u64 v[170:171], v[210:211], 0, s[8:9]
	s_addc_u32 s27, s37, 0
	s_add_i32 s36, s65, s43
	global_load_lds_dwordx4 v[170:171], off
	v_lshl_add_u64 v[170:171], s[26:27], 0, v[130:131]
	s_mov_b32 m0, s36
	s_nop 0
	global_load_lds_dwordx4 v[170:171], off
	v_lshl_add_u64 v[170:171], s[26:27], 0, v[134:135]
	s_add_i32 m0, s36, 0x2000
	s_nop 0
	global_load_lds_dwordx4 v[170:171], off
	v_lshl_add_u64 v[170:171], v[226:227], 0, s[8:9]
	s_mov_b32 m0, s49
	s_nop 0
	global_load_lds_dwordx4 v[170:171], off
	v_lshl_add_u64 v[170:171], v[228:229], 0, s[8:9]
	s_mov_b32 m0, s50
	s_nop 0
	global_load_lds_dwordx4 v[170:171], off
	s_waitcnt vmcnt(8)
	s_waitcnt lgkmcnt(0)
	v_mfma_f32_16x16x32_bf16 v[60:63], v[144:147], v[190:193], v[60:63]
	v_mfma_f32_16x16x32_bf16 v[56:59], v[158:161], v[190:193], v[56:59]
	s_barrier
	s_setprio 1
	s_waitcnt lgkmcnt(0)
	v_mfma_f32_16x16x32_bf16 v[52:55], v[144:147], v[198:201], v[52:55]
	v_mfma_f32_16x16x32_bf16 v[48:51], v[158:161], v[198:201], v[48:51]
	v_mfma_f32_16x16x32_bf16 v[28:31], v[144:147], v[206:209], v[28:31]
	v_mfma_f32_16x16x32_bf16 v[24:27], v[158:161], v[206:209], v[24:27]
	v_mfma_f32_16x16x32_bf16 v[16:19], v[144:147], v[218:221], v[16:19]
	v_mfma_f32_16x16x32_bf16 v[8:11], v[158:161], v[218:221], v[8:11]
	v_mfma_f32_16x16x32_bf16 v[60:63], v[148:151], v[194:197], v[60:63]
	v_mfma_f32_16x16x32_bf16 v[56:59], v[162:165], v[194:197], v[56:59]
	v_mfma_f32_16x16x32_bf16 v[52:55], v[148:151], v[202:205], v[52:55]
	v_mfma_f32_16x16x32_bf16 v[48:51], v[162:165], v[202:205], v[48:51]
	v_mfma_f32_16x16x32_bf16 v[28:31], v[148:151], v[214:217], v[28:31]
	v_mfma_f32_16x16x32_bf16 v[24:27], v[162:165], v[214:217], v[24:27]
	v_mfma_f32_16x16x32_bf16 v[16:19], v[148:151], v[222:225], v[16:19]
	v_mfma_f32_16x16x32_bf16 v[8:11], v[162:165], v[222:225], v[8:11]
	s_setprio 0
	s_setprio 1
	v_mfma_f32_16x16x32_bf16 v[44:47], v[166:169], v[190:193], v[44:47]
	v_mfma_f32_16x16x32_bf16 v[40:43], v[182:185], v[190:193], v[40:43]
	v_mfma_f32_16x16x32_bf16 v[36:39], v[166:169], v[198:201], v[36:39]
	v_mfma_f32_16x16x32_bf16 v[32:35], v[182:185], v[198:201], v[32:35]
	v_mfma_f32_16x16x32_bf16 v[20:23], v[166:169], v[206:209], v[20:23]
	v_mfma_f32_16x16x32_bf16 v[12:15], v[182:185], v[206:209], v[12:15]
	v_mfma_f32_16x16x32_bf16 v[4:7], v[166:169], v[218:221], v[4:7]
	v_mfma_f32_16x16x32_bf16 v[0:3], v[182:185], v[218:221], v[0:3]
	v_mfma_f32_16x16x32_bf16 v[44:47], v[178:181], v[194:197], v[44:47]
	v_mfma_f32_16x16x32_bf16 v[40:43], v[186:189], v[194:197], v[40:43]
	v_mfma_f32_16x16x32_bf16 v[36:39], v[178:181], v[202:205], v[36:39]
	v_mfma_f32_16x16x32_bf16 v[32:35], v[186:189], v[202:205], v[32:35]
	v_mfma_f32_16x16x32_bf16 v[20:23], v[178:181], v[214:217], v[20:23]
	v_mfma_f32_16x16x32_bf16 v[12:15], v[186:189], v[214:217], v[12:15]
	v_mfma_f32_16x16x32_bf16 v[4:7], v[178:181], v[222:225], v[4:7]
	v_mfma_f32_16x16x32_bf16 v[0:3], v[186:189], v[222:225], v[0:3]
	s_setprio 0
	s_barrier
	s_add_i32 s63, s63, 2
	s_add_u32 s58, s58, 0x100
	s_addc_u32 s59, s59, 0
	s_cmpk_gt_u32 s63, 0x55
	s_mov_b64 s[26:27], s[34:35]
	s_cbranch_scc0 .LBB0_550
	v_lshl_add_u32 v148, s56, 8, v152
	v_lshl_or_b32 v144, s57, 8, v154
	v_ashrrev_i32_e32 v149, 31, v148
	v_ashrrev_i32_e32 v145, 31, v144
	v_lshlrev_b64 v[146:147], 12, v[148:149]
	v_lshl_add_u64 v[150:151], s[14:15], 0, v[146:147]
	v_lshlrev_b64 v[144:145], 1, v[144:145]
	v_lshl_add_u64 v[150:151], v[150:151], 0, v[144:145]
	global_load_dwordx4 v[158:161], v[150:151], off
	global_load_dwordx4 v[162:165], v[150:151], off offset:256
	v_or_b32_e32 v150, 16, v148
	v_ashrrev_i32_e32 v151, 31, v150
	v_lshlrev_b64 v[170:171], 12, v[150:151]
	v_lshl_add_u64 v[150:151], s[14:15], 0, v[170:171]
	v_lshl_add_u64 v[150:151], v[150:151], 0, v[144:145]
	global_load_dwordx4 v[166:169], v[150:151], off
	global_load_dwordx4 v[178:181], v[150:151], off offset:256
	v_or_b32_e32 v150, 32, v148
	v_ashrrev_i32_e32 v151, 31, v150
	v_lshlrev_b64 v[150:151], 12, v[150:151]
	v_lshl_add_u64 v[182:183], s[14:15], 0, v[150:151]
	v_lshl_add_u64 v[186:187], v[182:183], 0, v[144:145]
	v_or_b32_e32 v148, 48, v148
	global_load_dwordx4 v[182:185], v[186:187], off
	v_ashrrev_i32_e32 v149, 31, v148
	v_lshl_add_u64 v[188:189], s[20:21], 0, v[146:147]
	v_lshlrev_b64 v[148:149], 12, v[148:149]
	v_lshl_add_u64 v[198:199], v[188:189], 0, v[144:145]
	v_lshl_add_u64 v[188:189], s[14:15], 0, v[148:149]
	v_lshl_add_u64 v[194:195], v[188:189], 0, v[144:145]
	global_load_dwordx4 v[186:189], v[186:187], off offset:256
	s_nop 0
	global_load_dwordx4 v[190:193], v[194:195], off
	s_nop 0
	global_load_dwordx4 v[194:197], v[194:195], off offset:256
	s_and_b64 vcc, exec, s[4:5]
	s_mov_b32 s57, s54
	s_mov_b32 s56, s55
	s_mov_b64 s[34:35], s[6:7]
	s_mov_b64 s[26:27], s[0:1]
	s_waitcnt vmcnt(0)
	v_lshlrev_b32_e32 v200, 16, v158
	v_and_b32_e32 v201, 0xffff0000, v158
	v_lshlrev_b32_e32 v158, 16, v159
	v_and_b32_e32 v159, 0xffff0000, v159
	v_lshlrev_b32_e32 v202, 16, v160
	v_and_b32_e32 v203, 0xffff0000, v160
	v_lshlrev_b32_e32 v160, 16, v161
	v_and_b32_e32 v161, 0xffff0000, v161
	v_lshlrev_b32_e32 v204, 16, v162
	v_and_b32_e32 v205, 0xffff0000, v162
	v_lshlrev_b32_e32 v162, 16, v163
	v_and_b32_e32 v163, 0xffff0000, v163
	v_lshlrev_b32_e32 v206, 16, v164
	v_and_b32_e32 v207, 0xffff0000, v164
	v_lshlrev_b32_e32 v164, 16, v165
	v_and_b32_e32 v165, 0xffff0000, v165
	v_lshlrev_b32_e32 v208, 16, v166
	v_and_b32_e32 v209, 0xffff0000, v166
	v_pk_add_f32 v[126:127], v[126:127], v[158:159]
	v_pk_add_f32 v[124:125], v[124:125], v[200:201]
	v_pk_add_f32 v[122:123], v[122:123], v[160:161]
	v_pk_add_f32 v[120:121], v[120:121], v[202:203]
	v_lshlrev_b32_e32 v166, 16, v167
	v_and_b32_e32 v167, 0xffff0000, v167
	v_pk_add_f32 v[110:111], v[110:111], v[162:163]
	v_pk_add_f32 v[108:109], v[108:109], v[204:205]
	v_pk_add_f32 v[158:159], v[106:107], v[164:165]
	v_pk_add_f32 v[160:161], v[104:105], v[206:207]
	v_cvt_pk_bf16_f32 v104, v124, v125
	v_cvt_pk_bf16_f32 v105, v126, v127
	v_cvt_pk_bf16_f32 v106, v120, v121
	v_cvt_pk_bf16_f32 v107, v122, v123
	v_pk_add_f32 v[116:117], v[116:117], v[208:209]
	v_cvt_pk_bf16_f32 v108, v108, v109
	v_cvt_pk_bf16_f32 v109, v110, v111
	v_cvt_pk_bf16_f32 v110, v160, v161
	v_cvt_pk_bf16_f32 v111, v158, v159
	v_pk_add_f32 v[118:119], v[118:119], v[166:167]
	global_store_dwordx4 v[198:199], v[104:107], off
	global_store_dwordx4 v[198:199], v[108:111], off offset:256
	v_lshlrev_b32_e32 v120, 16, v184
	v_cvt_pk_bf16_f32 v104, v116, v117
	v_lshlrev_b32_e32 v116, 16, v182
	v_and_b32_e32 v117, 0xffff0000, v182
	v_cvt_pk_bf16_f32 v105, v118, v119
	v_lshlrev_b32_e32 v118, 16, v183
	v_and_b32_e32 v119, 0xffff0000, v183
	v_and_b32_e32 v121, 0xffff0000, v184
	v_lshlrev_b32_e32 v122, 16, v185
	v_and_b32_e32 v123, 0xffff0000, v185
	v_pk_add_f32 v[92:93], v[92:93], v[116:117]
	v_pk_add_f32 v[94:95], v[94:95], v[118:119]
	v_pk_add_f32 v[116:117], v[90:91], v[122:123]
	v_pk_add_f32 v[90:91], v[88:89], v[120:121]
	v_cvt_pk_bf16_f32 v88, v92, v93
	v_lshl_add_u64 v[92:93], s[20:21], 0, v[150:151]
	v_lshlrev_b32_e32 v210, 16, v168
	v_and_b32_e32 v211, 0xffff0000, v168
	v_lshlrev_b32_e32 v168, 16, v169
	v_and_b32_e32 v169, 0xffff0000, v169
	v_lshlrev_b32_e32 v124, 16, v186
	v_and_b32_e32 v125, 0xffff0000, v186
	v_lshlrev_b32_e32 v126, 16, v187
	v_and_b32_e32 v127, 0xffff0000, v187
	v_lshlrev_b32_e32 v158, 16, v188
	v_and_b32_e32 v159, 0xffff0000, v188
	v_lshlrev_b32_e32 v160, 16, v189
	v_and_b32_e32 v161, 0xffff0000, v189
	v_cvt_pk_bf16_f32 v89, v94, v95
	v_cvt_pk_bf16_f32 v90, v90, v91
	v_cvt_pk_bf16_f32 v91, v116, v117
	v_lshl_add_u64 v[92:93], v[92:93], 0, v[144:145]
	v_pk_add_f32 v[114:115], v[114:115], v[168:169]
	v_pk_add_f32 v[112:113], v[112:113], v[210:211]
	v_lshl_add_u64 v[108:109], s[20:21], 0, v[170:171]
	global_store_dwordx4 v[92:93], v[88:91], off
	v_pk_add_f32 v[78:79], v[78:79], v[126:127]
	v_pk_add_f32 v[76:77], v[76:77], v[124:125]
	v_pk_add_f32 v[88:89], v[74:75], v[160:161]
	v_pk_add_f32 v[74:75], v[72:73], v[158:159]
	v_lshlrev_b32_e32 v214, 16, v178
	v_and_b32_e32 v215, 0xffff0000, v178
	v_lshlrev_b32_e32 v178, 16, v179
	v_and_b32_e32 v179, 0xffff0000, v179
	v_lshlrev_b32_e32 v216, 16, v180
	v_and_b32_e32 v217, 0xffff0000, v180
	v_lshlrev_b32_e32 v180, 16, v181
	v_and_b32_e32 v181, 0xffff0000, v181
	v_cvt_pk_bf16_f32 v106, v112, v113
	v_cvt_pk_bf16_f32 v107, v114, v115
	v_lshl_add_u64 v[108:109], v[108:109], 0, v[144:145]
	v_lshlrev_b32_e32 v162, 16, v190
	v_and_b32_e32 v163, 0xffff0000, v190
	v_lshlrev_b32_e32 v164, 16, v191
	v_and_b32_e32 v165, 0xffff0000, v191
	v_lshlrev_b32_e32 v168, 16, v193
	v_and_b32_e32 v169, 0xffff0000, v193
	v_cvt_pk_bf16_f32 v72, v76, v77
	v_cvt_pk_bf16_f32 v73, v78, v79
	v_cvt_pk_bf16_f32 v74, v74, v75
	v_cvt_pk_bf16_f32 v75, v88, v89
	global_store_dwordx4 v[108:109], v[104:107], off
	v_pk_add_f32 v[102:103], v[102:103], v[178:179]
	v_pk_add_f32 v[100:101], v[100:101], v[214:215]
	v_pk_add_f32 v[104:105], v[98:99], v[180:181]
	v_pk_add_f32 v[98:99], v[96:97], v[216:217]
	v_lshlrev_b32_e32 v166, 16, v192
	v_and_b32_e32 v167, 0xffff0000, v192
	global_store_dwordx4 v[92:93], v[72:75], off offset:256
	v_pk_add_f32 v[76:77], v[82:83], v[168:169]
	v_cvt_pk_bf16_f32 v96, v100, v101
	v_pk_add_f32 v[74:75], v[86:87], v[164:165]
	v_pk_add_f32 v[72:73], v[84:85], v[162:163]
	v_cvt_pk_bf16_f32 v97, v102, v103
	v_cvt_pk_bf16_f32 v98, v98, v99
	v_cvt_pk_bf16_f32 v99, v104, v105
	v_lshlrev_b32_e32 v170, 16, v194
	v_and_b32_e32 v171, 0xffff0000, v194
	v_pk_add_f32 v[78:79], v[80:81], v[166:167]
	v_cvt_pk_bf16_f32 v72, v72, v73
	v_cvt_pk_bf16_f32 v73, v74, v75
	v_cvt_pk_bf16_f32 v75, v76, v77
	v_lshl_add_u64 v[76:77], s[20:21], 0, v[148:149]
	global_store_dwordx4 v[108:109], v[96:99], off offset:256
	v_lshlrev_b32_e32 v178, 16, v195
	v_and_b32_e32 v179, 0xffff0000, v195
	v_lshl_add_u64 v[96:97], v[146:147], 0, s[12:13]
	v_lshlrev_b32_e32 v180, 16, v196
	v_and_b32_e32 v181, 0xffff0000, v196
	v_lshlrev_b32_e32 v182, 16, v197
	v_and_b32_e32 v183, 0xffff0000, v197
	v_cvt_pk_bf16_f32 v74, v78, v79
	v_lshl_add_u64 v[76:77], v[76:77], 0, v[144:145]
	v_pk_add_f32 v[68:69], v[68:69], v[170:171]
	v_lshl_add_u64 v[80:81], v[146:147], 0, s[22:23]
	v_lshl_add_u64 v[98:99], s[14:15], 0, v[96:97]
	global_store_dwordx4 v[76:77], v[72:75], off
	v_pk_add_f32 v[70:71], v[70:71], v[178:179]
	v_lshl_add_u64 v[98:99], v[98:99], 0, v[144:145]
	v_pk_add_f32 v[72:73], v[66:67], v[182:183]
	v_pk_add_f32 v[66:67], v[64:65], v[180:181]
	v_cvt_pk_bf16_f32 v64, v68, v69
	v_lshl_add_u64 v[68:69], s[14:15], 0, v[80:81]
	v_cvt_pk_bf16_f32 v65, v70, v71
	v_cvt_pk_bf16_f32 v66, v66, v67
	v_cvt_pk_bf16_f32 v67, v72, v73
	v_lshl_add_u64 v[72:73], v[68:69], 0, v[144:145]
	v_lshl_add_u64 v[92:93], v[146:147], 0, s[24:25]
	global_load_dwordx4 v[100:103], v[98:99], off
	global_load_dwordx4 v[68:71], v[72:73], off
	global_load_dwordx4 v[104:107], v[98:99], off offset:256
	s_nop 0
	global_store_dwordx4 v[76:77], v[64:67], off offset:256
	global_load_dwordx4 v[64:67], v[72:73], off offset:256
	v_lshl_add_u64 v[72:73], s[14:15], 0, v[92:93]
	v_lshl_add_u64 v[76:77], v[72:73], 0, v[144:145]
	global_load_dwordx4 v[72:75], v[76:77], off
	s_waitcnt vmcnt(5)
	v_lshlrev_b32_e32 v82, 16, v100
	global_load_dwordx4 v[76:79], v[76:77], off offset:256
	v_lshl_add_u64 v[98:99], v[146:147], 0, s[18:19]
	v_lshl_add_u64 v[108:109], s[14:15], 0, v[98:99]
	v_lshl_add_u64 v[112:113], v[108:109], 0, v[144:145]
	global_load_dwordx4 v[108:111], v[112:113], off
	v_and_b32_e32 v83, 0xffff0000, v100
	global_load_dwordx4 v[112:115], v[112:113], off offset:256
	v_lshlrev_b32_e32 v84, 16, v101
	v_and_b32_e32 v85, 0xffff0000, v101
	v_lshlrev_b32_e32 v86, 16, v102
	v_and_b32_e32 v87, 0xffff0000, v102
	v_lshlrev_b32_e32 v88, 16, v103
	v_and_b32_e32 v89, 0xffff0000, v103
	v_pk_add_f32 v[60:61], v[60:61], v[82:83]
	v_pk_add_f32 v[62:63], v[62:63], v[84:85]
	v_pk_add_f32 v[82:83], v[58:59], v[88:89]
	v_pk_add_f32 v[58:59], v[56:57], v[86:87]
	v_cvt_pk_bf16_f32 v56, v60, v61
	v_lshl_add_u64 v[60:61], s[20:21], 0, v[96:97]
	s_waitcnt vmcnt(6)
	v_lshlrev_b32_e32 v90, 16, v104
	v_and_b32_e32 v91, 0xffff0000, v104
	v_lshlrev_b32_e32 v94, 16, v105
	v_and_b32_e32 v95, 0xffff0000, v105
	v_lshlrev_b32_e32 v100, 16, v106
	v_and_b32_e32 v101, 0xffff0000, v106
	v_lshlrev_b32_e32 v102, 16, v107
	v_and_b32_e32 v103, 0xffff0000, v107
	v_cvt_pk_bf16_f32 v57, v62, v63
	v_cvt_pk_bf16_f32 v58, v58, v59
	v_cvt_pk_bf16_f32 v59, v82, v83
	v_lshl_add_u64 v[60:61], v[60:61], 0, v[144:145]
	global_store_dwordx4 v[60:61], v[56:59], off
	v_pk_add_f32 v[46:47], v[46:47], v[94:95]
	v_pk_add_f32 v[44:45], v[44:45], v[90:91]
	v_pk_add_f32 v[56:57], v[42:43], v[102:103]
	v_pk_add_f32 v[42:43], v[40:41], v[100:101]
	v_cvt_pk_bf16_f32 v40, v44, v45
	v_cvt_pk_bf16_f32 v41, v46, v47
	v_cvt_pk_bf16_f32 v42, v42, v43
	v_cvt_pk_bf16_f32 v43, v56, v57
	global_store_dwordx4 v[60:61], v[40:43], off offset:256
	s_waitcnt vmcnt(4)
	v_lshlrev_b32_e32 v56, 16, v76
	v_and_b32_e32 v57, 0xffff0000, v76
	v_lshlrev_b32_e32 v58, 16, v77
	v_and_b32_e32 v59, 0xffff0000, v77
	s_waitcnt vmcnt(3)
	v_lshlrev_b32_e32 v104, 16, v108
	v_and_b32_e32 v105, 0xffff0000, v108
	v_lshlrev_b32_e32 v106, 16, v109
	v_and_b32_e32 v107, 0xffff0000, v109
	v_lshlrev_b32_e32 v108, 16, v110
	v_and_b32_e32 v109, 0xffff0000, v110
	v_lshlrev_b32_e32 v110, 16, v111
	v_and_b32_e32 v111, 0xffff0000, v111
	v_pk_add_f32 v[42:43], v[54:55], v[106:107]
	v_pk_add_f32 v[40:41], v[52:53], v[104:105]
	v_pk_add_f32 v[44:45], v[50:51], v[110:111]
	v_pk_add_f32 v[46:47], v[48:49], v[108:109]
	v_cvt_pk_bf16_f32 v40, v40, v41
	v_cvt_pk_bf16_f32 v41, v42, v43
	v_cvt_pk_bf16_f32 v43, v44, v45
	v_lshl_add_u64 v[44:45], s[20:21], 0, v[98:99]
	s_waitcnt vmcnt(2)
	v_lshlrev_b32_e32 v116, 16, v112
	v_and_b32_e32 v117, 0xffff0000, v112
	v_lshlrev_b32_e32 v112, 16, v113
	v_and_b32_e32 v113, 0xffff0000, v113
	v_lshlrev_b32_e32 v118, 16, v114
	v_and_b32_e32 v119, 0xffff0000, v114
	v_lshlrev_b32_e32 v114, 16, v115
	v_and_b32_e32 v115, 0xffff0000, v115
	v_cvt_pk_bf16_f32 v42, v46, v47
	v_lshl_add_u64 v[44:45], v[44:45], 0, v[144:145]
	global_store_dwordx4 v[44:45], v[40:43], off
	v_pk_add_f32 v[38:39], v[38:39], v[112:113]
	v_pk_add_f32 v[36:37], v[36:37], v[116:117]
	v_pk_add_f32 v[40:41], v[34:35], v[114:115]
	v_pk_add_f32 v[34:35], v[32:33], v[118:119]
	v_cvt_pk_bf16_f32 v32, v36, v37
	v_cvt_pk_bf16_f32 v33, v38, v39
	v_cvt_pk_bf16_f32 v34, v34, v35
	v_cvt_pk_bf16_f32 v35, v40, v41
	global_store_dwordx4 v[44:45], v[32:35], off offset:256
	v_lshlrev_b32_e32 v36, 16, v70
	v_and_b32_e32 v37, 0xffff0000, v70
	v_lshlrev_b32_e32 v32, 16, v68
	v_and_b32_e32 v33, 0xffff0000, v68
	v_lshlrev_b32_e32 v34, 16, v69
	v_and_b32_e32 v35, 0xffff0000, v69
	v_lshlrev_b32_e32 v38, 16, v71
	v_and_b32_e32 v39, 0xffff0000, v71
	v_pk_add_f32 v[28:29], v[28:29], v[32:33]
	v_pk_add_f32 v[30:31], v[30:31], v[34:35]
	v_pk_add_f32 v[32:33], v[26:27], v[38:39]
	v_pk_add_f32 v[26:27], v[24:25], v[36:37]
	v_cvt_pk_bf16_f32 v24, v28, v29
	v_lshl_add_u64 v[28:29], s[20:21], 0, v[80:81]
	v_lshlrev_b32_e32 v40, 16, v64
	v_and_b32_e32 v41, 0xffff0000, v64
	v_lshlrev_b32_e32 v42, 16, v65
	v_and_b32_e32 v43, 0xffff0000, v65
	v_lshlrev_b32_e32 v44, 16, v66
	v_and_b32_e32 v45, 0xffff0000, v66
	v_lshlrev_b32_e32 v46, 16, v67
	v_and_b32_e32 v47, 0xffff0000, v67
	v_cvt_pk_bf16_f32 v25, v30, v31
	v_cvt_pk_bf16_f32 v26, v26, v27
	v_cvt_pk_bf16_f32 v27, v32, v33
	v_lshl_add_u64 v[28:29], v[28:29], 0, v[144:145]
	global_store_dwordx4 v[28:29], v[24:27], off
	v_pk_add_f32 v[22:23], v[22:23], v[42:43]
	v_pk_add_f32 v[20:21], v[20:21], v[40:41]
	v_pk_add_f32 v[24:25], v[14:15], v[46:47]
	v_pk_add_f32 v[14:15], v[12:13], v[44:45]
	v_lshlrev_b32_e32 v50, 16, v73
	v_and_b32_e32 v51, 0xffff0000, v73
	v_cvt_pk_bf16_f32 v12, v20, v21
	v_cvt_pk_bf16_f32 v13, v22, v23
	v_cvt_pk_bf16_f32 v14, v14, v15
	v_cvt_pk_bf16_f32 v15, v24, v25
	v_lshlrev_b32_e32 v48, 16, v72
	v_and_b32_e32 v49, 0xffff0000, v72
	v_lshlrev_b32_e32 v52, 16, v74
	v_and_b32_e32 v53, 0xffff0000, v74
	v_lshlrev_b32_e32 v54, 16, v75
	v_and_b32_e32 v55, 0xffff0000, v75
	global_store_dwordx4 v[28:29], v[12:15], off offset:256
	v_lshlrev_b32_e32 v60, 16, v78
	v_and_b32_e32 v61, 0xffff0000, v78
	v_pk_add_f32 v[12:13], v[18:19], v[50:51]
	v_pk_add_f32 v[14:15], v[16:17], v[48:49]
	v_pk_add_f32 v[16:17], v[10:11], v[54:55]
	v_pk_add_f32 v[10:11], v[8:9], v[52:53]
	v_cvt_pk_bf16_f32 v9, v12, v13
	v_lshl_add_u64 v[12:13], s[20:21], 0, v[92:93]
	v_lshlrev_b32_e32 v62, 16, v79
	v_and_b32_e32 v63, 0xffff0000, v79
	v_cvt_pk_bf16_f32 v8, v14, v15
	v_cvt_pk_bf16_f32 v10, v10, v11
	v_cvt_pk_bf16_f32 v11, v16, v17
	v_lshl_add_u64 v[12:13], v[12:13], 0, v[144:145]
	global_store_dwordx4 v[12:13], v[8:11], off
	v_pk_add_f32 v[6:7], v[6:7], v[58:59]
	v_pk_add_f32 v[4:5], v[4:5], v[56:57]
	v_pk_add_f32 v[8:9], v[2:3], v[62:63]
	v_pk_add_f32 v[2:3], v[0:1], v[60:61]
	v_cvt_pk_bf16_f32 v0, v4, v5
	v_cvt_pk_bf16_f32 v1, v6, v7
	v_cvt_pk_bf16_f32 v2, v2, v3
	v_cvt_pk_bf16_f32 v3, v8, v9
	global_store_dwordx4 v[12:13], v[0:3], off offset:256
	s_cbranch_vccz .LBB0_539
	s_waitcnt vmcnt(0)
	s_cmpk_gt_u32 s40, 0xff
	s_cbranch_scc1 .LBB0_554
	s_barrier

	.amdhsa_kernel _Z10hybrid_fwd6Params
		.amdhsa_group_segment_fixed_size 0
		.amdhsa_private_segment_fixed_size 0
		.amdhsa_kernarg_size 440
		.amdhsa_user_sgpr_count 2
		.amdhsa_user_sgpr_dispatch_ptr 0
		.amdhsa_user_sgpr_queue_ptr 0
		.amdhsa_user_sgpr_kernarg_segment_ptr 1
		.amdhsa_user_sgpr_dispatch_id 0
		.amdhsa_user_sgpr_kernarg_preload_length 0
		.amdhsa_user_sgpr_kernarg_preload_offset 0
		.amdhsa_user_sgpr_private_segment_size 0
		.amdhsa_uses_dynamic_stack 0
		.amdhsa_enable_private_segment 0
		.amdhsa_system_sgpr_workgroup_id_x 1
		.amdhsa_system_sgpr_workgroup_id_y 0
		.amdhsa_system_sgpr_workgroup_id_z 0
		.amdhsa_system_sgpr_workgroup_info 0
		.amdhsa_system_vgpr_workitem_id 2
		.amdhsa_next_free_vgpr 252
		.amdhsa_next_free_sgpr 91
		.amdhsa_accum_offset 252
		.amdhsa_reserve_vcc 1
		.amdhsa_float_round_mode_32 0
		.amdhsa_float_round_mode_16_64 0
		.amdhsa_float_denorm_mode_32 3
		.amdhsa_float_denorm_mode_16_64 3
		.amdhsa_dx10_clamp 1
		.amdhsa_ieee_mode 1
		.amdhsa_fp16_overflow 0
		.amdhsa_tg_split 0
		.amdhsa_exception_fp_ieee_invalid_op 0
		.amdhsa_exception_fp_denorm_src 0
		.amdhsa_exception_fp_ieee_div_zero 0
		.amdhsa_exception_fp_ieee_overflow 0
		.amdhsa_exception_fp_ieee_underflow 0
		.amdhsa_exception_fp_ieee_inexact 0
		.amdhsa_exception_int_div_zero 0
	.end_amdhsa_kernel

amdhsa.kernels:
  - .agpr_count:     0
    .args:
      - .offset:         0
        .size:           184
        .value_kind:     by_value
      - .offset:         184
        .size:           4
        .value_kind:     hidden_block_count_x
      - .offset:         188
        .size:           4
        .value_kind:     hidden_block_count_y
      - .offset:         192
        .size:           4
        .value_kind:     hidden_block_count_z
      - .offset:         196
        .size:           2
        .value_kind:     hidden_group_size_x
      - .offset:         198
        .size:           2
        .value_kind:     hidden_group_size_y
      - .offset:         200
        .size:           2
        .value_kind:     hidden_group_size_z
      - .offset:         202
        .size:           2
        .value_kind:     hidden_remainder_x
      - .offset:         204
        .size:           2
        .value_kind:     hidden_remainder_y
      - .offset:         206
        .size:           2
        .value_kind:     hidden_remainder_z
      - .offset:         224
        .size:           8
        .value_kind:     hidden_global_offset_x
      - .offset:         232
        .size:           8
        .value_kind:     hidden_global_offset_y
      - .offset:         240
        .size:           8
        .value_kind:     hidden_global_offset_z
      - .offset:         248
        .size:           2
        .value_kind:     hidden_grid_dims
      - .offset:         272
        .size:           8
        .value_kind:     hidden_multigrid_sync_arg
      - .offset:         304
        .size:           4
        .value_kind:     hidden_dynamic_lds_size
    .group_segment_fixed_size: 0
    .kernarg_segment_align: 8
    .kernarg_segment_size: 440
    .language:       OpenCL C
    .language_version:
      - 2
      - 0
    .max_flat_workgroup_size: 512
    .name:           _Z10hybrid_fwd6Params
    .private_segment_fixed_size: 0
    .sgpr_count:     97
    .sgpr_spill_count: 0
    .symbol:         _Z10hybrid_fwd6Params.kd
    .uniform_work_group_size: 1
    .uses_dynamic_stack: false
    .vgpr_count:     252
    .vgpr_spill_count: 0
    .wavefront_size: 64
